# A-major order of the chained same-accumulator MFMA pairs in all live bf16 K-loops
# speedup vs baseline: 1.0201x; 1.0075x over previous
.LBB0_1516:
	v_add_u32_e32 v156, s83, v142
	v_add_u32_e32 v172, s44, v142
	s_add_u32 s8, s37, s6
	ds_read_b128 v[144:147], v156
	ds_read_b128 v[148:151], v156 offset:1024
	ds_read_b128 v[152:155], v156 offset:2048
	ds_read_b128 v[156:159], v156 offset:3072
	ds_read_b128 v[160:163], v172
	ds_read_b128 v[164:167], v172 offset:1024
	ds_read_b128 v[168:171], v172 offset:2048
	ds_read_b128 v[172:175], v172 offset:3072
	s_addc_u32 s9, s40, s7
	s_add_u32 s8, s8, 0x20400100
	s_addc_u32 s9, s9, 0
	s_add_u32 s46, s41, s6
	s_addc_u32 s47, s42, s7
	s_cmpk_eq_i32 s6, 0xf00
	s_cselect_b32 s11, s5, s9
	s_cselect_b32 s10, s4, s8
	s_cselect_b32 s9, s3, s47
	s_cselect_b32 s8, s2, s46
	v_lshl_add_u64 v[208:209], v[138:139], 0, s[6:7]
	s_add_i32 m0, s16, 0xc000
	ds_read_b128 v[176:179], v143
	ds_read_b128 v[180:183], v143 offset:1024
	ds_read_b128 v[184:187], v143 offset:2048
	ds_read_b128 v[188:191], v143 offset:3072
	ds_read_b128 v[192:195], v143 offset:4096
	ds_read_b128 v[196:199], v143 offset:5120
	ds_read_b128 v[200:203], v143 offset:6144
	ds_read_b128 v[204:207], v143 offset:7168
	global_load_lds_dwordx4 v[208:209], off
	v_lshl_add_u64 v[208:209], v[140:141], 0, s[6:7]
	s_add_i32 m0, s16, 0xe000
	s_nop 0
	global_load_lds_dwordx4 v[208:209], off
	s_waitcnt vmcnt(8)
	s_waitcnt lgkmcnt(0)
	s_barrier
	s_setprio 1
	s_waitcnt lgkmcnt(0)
	v_mfma_f32_16x16x32_bf16 v[128:131], v[144:147], v[176:179], v[128:131]
	v_mfma_f32_16x16x32_bf16 v[128:131], v[148:151], v[180:183], v[128:131]
	v_mfma_f32_16x16x32_bf16 v[112:115], v[144:147], v[184:187], v[112:115]
	v_mfma_f32_16x16x32_bf16 v[112:115], v[148:151], v[188:191], v[112:115]
	v_mfma_f32_16x16x32_bf16 v[96:99], v[144:147], v[192:195], v[96:99]
	v_mfma_f32_16x16x32_bf16 v[96:99], v[148:151], v[196:199], v[96:99]
	v_mfma_f32_16x16x32_bf16 v[80:83], v[144:147], v[200:203], v[80:83]
	v_mfma_f32_16x16x32_bf16 v[80:83], v[148:151], v[204:207], v[80:83]
	v_mfma_f32_16x16x32_bf16 v[124:127], v[152:155], v[176:179], v[124:127]
	v_mfma_f32_16x16x32_bf16 v[124:127], v[156:159], v[180:183], v[124:127]
	v_mfma_f32_16x16x32_bf16 v[108:111], v[152:155], v[184:187], v[108:111]
	v_mfma_f32_16x16x32_bf16 v[108:111], v[156:159], v[188:191], v[108:111]
	v_mfma_f32_16x16x32_bf16 v[92:95], v[152:155], v[192:195], v[92:95]
	v_mfma_f32_16x16x32_bf16 v[92:95], v[156:159], v[196:199], v[92:95]
	v_mfma_f32_16x16x32_bf16 v[76:79], v[152:155], v[200:203], v[76:79]
	v_mfma_f32_16x16x32_bf16 v[76:79], v[156:159], v[204:207], v[76:79]
	s_setprio 0
	s_setprio 1
	v_mfma_f32_16x16x32_bf16 v[120:123], v[160:163], v[176:179], v[120:123]
	v_mfma_f32_16x16x32_bf16 v[120:123], v[164:167], v[180:183], v[120:123]
	v_mfma_f32_16x16x32_bf16 v[104:107], v[160:163], v[184:187], v[104:107]
	v_mfma_f32_16x16x32_bf16 v[104:107], v[164:167], v[188:191], v[104:107]
	v_mfma_f32_16x16x32_bf16 v[88:91], v[160:163], v[192:195], v[88:91]
	v_mfma_f32_16x16x32_bf16 v[88:91], v[164:167], v[196:199], v[88:91]
	v_mfma_f32_16x16x32_bf16 v[72:75], v[160:163], v[200:203], v[72:75]
	v_mfma_f32_16x16x32_bf16 v[72:75], v[164:167], v[204:207], v[72:75]
	v_mfma_f32_16x16x32_bf16 v[116:119], v[168:171], v[176:179], v[116:119]
	v_mfma_f32_16x16x32_bf16 v[116:119], v[172:175], v[180:183], v[116:119]
	v_mfma_f32_16x16x32_bf16 v[100:103], v[168:171], v[184:187], v[100:103]
	v_mfma_f32_16x16x32_bf16 v[100:103], v[172:175], v[188:191], v[100:103]
	v_mfma_f32_16x16x32_bf16 v[84:87], v[168:171], v[192:195], v[84:87]
	v_mfma_f32_16x16x32_bf16 v[84:87], v[172:175], v[196:199], v[84:87]
	v_mfma_f32_16x16x32_bf16 v[68:71], v[168:171], v[200:203], v[68:71]
	v_mfma_f32_16x16x32_bf16 v[68:71], v[172:175], v[204:207], v[68:71]
	s_setprio 0
	s_barrier
	s_mov_b32 m0, s13
	v_lshl_add_u64 v[208:209], s[8:9], 0, v[2:3]
	s_add_u32 s46, s8, 0x80000
	ds_read_b128 v[176:179], v143 offset:16384
	ds_read_b128 v[180:183], v143 offset:17408
	ds_read_b128 v[184:187], v143 offset:18432
	ds_read_b128 v[188:191], v143 offset:19456
	ds_read_b128 v[192:195], v143 offset:20480
	ds_read_b128 v[196:199], v143 offset:21504
	ds_read_b128 v[200:203], v143 offset:22528
	ds_read_b128 v[204:207], v143 offset:23552
	global_load_lds_dwordx4 v[208:209], off
	v_lshl_add_u64 v[210:211], s[8:9], 0, v[136:137]
	s_mov_b32 m0, s14
	s_addc_u32 s47, s9, 0
	global_load_lds_dwordx4 v[210:211], off
	v_lshl_add_u64 v[216:217], s[46:47], 0, v[2:3]
	s_mov_b32 m0, s15
	v_lshl_add_u64 v[218:219], s[10:11], 0, v[134:135]
	global_load_lds_dwordx4 v[216:217], off
	v_lshl_add_u64 v[216:217], s[46:47], 0, v[136:137]
	s_mov_b32 m0, s19
	s_nop 0
	global_load_lds_dwordx4 v[216:217], off
	v_lshl_add_u64 v[216:217], s[10:11], 0, v[132:133]
	s_mov_b32 m0, s16
	s_nop 0
	global_load_lds_dwordx4 v[216:217], off
	s_mov_b32 m0, s20
	s_nop 0
	global_load_lds_dwordx4 v[218:219], off
	s_waitcnt vmcnt(8)
	s_waitcnt lgkmcnt(0)
	s_barrier
	s_setprio 1
	s_waitcnt lgkmcnt(0)
	v_mfma_f32_16x16x32_bf16 v[64:67], v[144:147], v[176:179], v[64:67]
	v_mfma_f32_16x16x32_bf16 v[64:67], v[148:151], v[180:183], v[64:67]
	v_mfma_f32_16x16x32_bf16 v[48:51], v[144:147], v[184:187], v[48:51]
	v_mfma_f32_16x16x32_bf16 v[48:51], v[148:151], v[188:191], v[48:51]
	v_mfma_f32_16x16x32_bf16 v[32:35], v[144:147], v[192:195], v[32:35]
	v_mfma_f32_16x16x32_bf16 v[32:35], v[148:151], v[196:199], v[32:35]
	v_mfma_f32_16x16x32_bf16 v[16:19], v[144:147], v[200:203], v[16:19]
	v_mfma_f32_16x16x32_bf16 v[16:19], v[148:151], v[204:207], v[16:19]
	v_mfma_f32_16x16x32_bf16 v[60:63], v[152:155], v[176:179], v[60:63]
	v_mfma_f32_16x16x32_bf16 v[60:63], v[156:159], v[180:183], v[60:63]
	v_mfma_f32_16x16x32_bf16 v[44:47], v[152:155], v[184:187], v[44:47]
	v_mfma_f32_16x16x32_bf16 v[44:47], v[156:159], v[188:191], v[44:47]
	v_mfma_f32_16x16x32_bf16 v[28:31], v[152:155], v[192:195], v[28:31]
	v_mfma_f32_16x16x32_bf16 v[28:31], v[156:159], v[196:199], v[28:31]
	v_mfma_f32_16x16x32_bf16 v[12:15], v[152:155], v[200:203], v[12:15]
	v_mfma_f32_16x16x32_bf16 v[12:15], v[156:159], v[204:207], v[12:15]
	s_setprio 0
	s_setprio 1
	v_mfma_f32_16x16x32_bf16 v[56:59], v[160:163], v[176:179], v[56:59]
	v_mfma_f32_16x16x32_bf16 v[56:59], v[164:167], v[180:183], v[56:59]
	v_mfma_f32_16x16x32_bf16 v[40:43], v[160:163], v[184:187], v[40:43]
	v_mfma_f32_16x16x32_bf16 v[40:43], v[164:167], v[188:191], v[40:43]
	v_mfma_f32_16x16x32_bf16 v[24:27], v[160:163], v[192:195], v[24:27]
	v_mfma_f32_16x16x32_bf16 v[24:27], v[164:167], v[196:199], v[24:27]
	v_mfma_f32_16x16x32_bf16 v[8:11], v[160:163], v[200:203], v[8:11]
	v_mfma_f32_16x16x32_bf16 v[8:11], v[164:167], v[204:207], v[8:11]
	v_mfma_f32_16x16x32_bf16 v[52:55], v[168:171], v[176:179], v[52:55]
	v_mfma_f32_16x16x32_bf16 v[52:55], v[172:175], v[180:183], v[52:55]
	v_mfma_f32_16x16x32_bf16 v[36:39], v[168:171], v[184:187], v[36:39]
	v_mfma_f32_16x16x32_bf16 v[36:39], v[172:175], v[188:191], v[36:39]
	v_mfma_f32_16x16x32_bf16 v[20:23], v[168:171], v[192:195], v[20:23]
	v_mfma_f32_16x16x32_bf16 v[20:23], v[172:175], v[196:199], v[20:23]
	v_mfma_f32_16x16x32_bf16 v[4:7], v[168:171], v[200:203], v[4:7]
	v_mfma_f32_16x16x32_bf16 v[4:7], v[172:175], v[204:207], v[4:7]
	s_setprio 0
	s_barrier
	v_add_u32_e32 v156, s45, v142
	v_add_u32_e32 v172, s74, v142
	ds_read_b128 v[144:147], v156
	ds_read_b128 v[148:151], v156 offset:1024
	ds_read_b128 v[152:155], v156 offset:2048
	ds_read_b128 v[156:159], v156 offset:3072
	ds_read_b128 v[160:163], v172
	ds_read_b128 v[164:167], v172 offset:1024
	ds_read_b128 v[168:171], v172 offset:2048
	ds_read_b128 v[172:175], v172 offset:3072
	s_add_u32 s10, s10, 0x80000
	s_addc_u32 s11, s11, 0
	s_mov_b32 m0, s22
	v_lshl_add_u64 v[220:221], s[10:11], 0, v[132:133]
	ds_read_b128 v[176:179], v143 offset:32768
	ds_read_b128 v[180:183], v143 offset:33792
	ds_read_b128 v[184:187], v143 offset:34816
	ds_read_b128 v[188:191], v143 offset:35840
	ds_read_b128 v[192:195], v143 offset:36864
	ds_read_b128 v[196:199], v143 offset:37888
	ds_read_b128 v[200:203], v143 offset:38912
	ds_read_b128 v[204:207], v143 offset:39936
	global_load_lds_dwordx4 v[220:221], off
	v_lshl_add_u64 v[220:221], s[10:11], 0, v[134:135]
	s_mov_b32 m0, s23
	s_nop 0
	global_load_lds_dwordx4 v[220:221], off
	s_waitcnt vmcnt(8)
	s_waitcnt lgkmcnt(0)
	s_barrier
	s_setprio 1
	s_waitcnt lgkmcnt(0)
	v_mfma_f32_16x16x32_bf16 v[128:131], v[144:147], v[176:179], v[128:131]
	v_mfma_f32_16x16x32_bf16 v[128:131], v[148:151], v[180:183], v[128:131]
	v_mfma_f32_16x16x32_bf16 v[112:115], v[144:147], v[184:187], v[112:115]
	v_mfma_f32_16x16x32_bf16 v[112:115], v[148:151], v[188:191], v[112:115]
	v_mfma_f32_16x16x32_bf16 v[96:99], v[144:147], v[192:195], v[96:99]
	v_mfma_f32_16x16x32_bf16 v[96:99], v[148:151], v[196:199], v[96:99]
	v_mfma_f32_16x16x32_bf16 v[80:83], v[144:147], v[200:203], v[80:83]
	v_mfma_f32_16x16x32_bf16 v[80:83], v[148:151], v[204:207], v[80:83]
	v_mfma_f32_16x16x32_bf16 v[124:127], v[152:155], v[176:179], v[124:127]
	v_mfma_f32_16x16x32_bf16 v[124:127], v[156:159], v[180:183], v[124:127]
	v_mfma_f32_16x16x32_bf16 v[108:111], v[152:155], v[184:187], v[108:111]
	v_mfma_f32_16x16x32_bf16 v[108:111], v[156:159], v[188:191], v[108:111]
	v_mfma_f32_16x16x32_bf16 v[92:95], v[152:155], v[192:195], v[92:95]
	v_mfma_f32_16x16x32_bf16 v[92:95], v[156:159], v[196:199], v[92:95]
	v_mfma_f32_16x16x32_bf16 v[76:79], v[152:155], v[200:203], v[76:79]
	v_mfma_f32_16x16x32_bf16 v[76:79], v[156:159], v[204:207], v[76:79]
	s_setprio 0
	s_setprio 1
	v_mfma_f32_16x16x32_bf16 v[120:123], v[160:163], v[176:179], v[120:123]
	v_mfma_f32_16x16x32_bf16 v[120:123], v[164:167], v[180:183], v[120:123]
	v_mfma_f32_16x16x32_bf16 v[104:107], v[160:163], v[184:187], v[104:107]
	v_mfma_f32_16x16x32_bf16 v[104:107], v[164:167], v[188:191], v[104:107]
	v_mfma_f32_16x16x32_bf16 v[88:91], v[160:163], v[192:195], v[88:91]
	v_mfma_f32_16x16x32_bf16 v[88:91], v[164:167], v[196:199], v[88:91]
	v_mfma_f32_16x16x32_bf16 v[72:75], v[160:163], v[200:203], v[72:75]
	v_mfma_f32_16x16x32_bf16 v[72:75], v[164:167], v[204:207], v[72:75]
	v_mfma_f32_16x16x32_bf16 v[116:119], v[168:171], v[176:179], v[116:119]
	v_mfma_f32_16x16x32_bf16 v[116:119], v[172:175], v[180:183], v[116:119]
	v_mfma_f32_16x16x32_bf16 v[100:103], v[168:171], v[184:187], v[100:103]
	v_mfma_f32_16x16x32_bf16 v[100:103], v[172:175], v[188:191], v[100:103]
	v_mfma_f32_16x16x32_bf16 v[84:87], v[168:171], v[192:195], v[84:87]
	v_mfma_f32_16x16x32_bf16 v[84:87], v[172:175], v[196:199], v[84:87]
	v_mfma_f32_16x16x32_bf16 v[68:71], v[168:171], v[200:203], v[68:71]
	v_mfma_f32_16x16x32_bf16 v[68:71], v[172:175], v[204:207], v[68:71]
	s_setprio 0
	s_barrier
	s_mov_b32 m0, s24
	v_lshl_add_u64 v[208:209], v[208:209], 0, s[64:65]
	s_add_u32 s8, s8, 0x80080
	ds_read_b128 v[176:179], v143 offset:49152
	ds_read_b128 v[180:183], v143 offset:50176
	ds_read_b128 v[184:187], v143 offset:51200
	ds_read_b128 v[188:191], v143 offset:52224
	ds_read_b128 v[192:195], v143 offset:53248
	ds_read_b128 v[196:199], v143 offset:54272
	ds_read_b128 v[200:203], v143 offset:55296
	ds_read_b128 v[204:207], v143 offset:56320
	global_load_lds_dwordx4 v[208:209], off
	v_lshl_add_u64 v[208:209], v[210:211], 0, s[64:65]
	s_mov_b32 m0, s25
	s_addc_u32 s9, s9, 0
	global_load_lds_dwordx4 v[208:209], off
	v_lshl_add_u64 v[208:209], s[8:9], 0, v[2:3]
	s_mov_b32 m0, s34
	s_nop 0
	global_load_lds_dwordx4 v[208:209], off
	v_lshl_add_u64 v[208:209], s[8:9], 0, v[136:137]
	s_mov_b32 m0, s35
	s_nop 0
	global_load_lds_dwordx4 v[208:209], off
	v_lshl_add_u64 v[208:209], v[216:217], 0, s[64:65]
	s_mov_b32 m0, s26
	s_nop 0
	global_load_lds_dwordx4 v[208:209], off
	v_lshl_add_u64 v[208:209], v[218:219], 0, s[64:65]
	s_mov_b32 m0, s27
	s_nop 0
	global_load_lds_dwordx4 v[208:209], off
	s_waitcnt vmcnt(8)
	s_waitcnt lgkmcnt(0)
	s_barrier
	s_setprio 1
	s_waitcnt lgkmcnt(0)
	v_mfma_f32_16x16x32_bf16 v[64:67], v[144:147], v[176:179], v[64:67]
	v_mfma_f32_16x16x32_bf16 v[64:67], v[148:151], v[180:183], v[64:67]
	v_mfma_f32_16x16x32_bf16 v[48:51], v[144:147], v[184:187], v[48:51]
	v_mfma_f32_16x16x32_bf16 v[48:51], v[148:151], v[188:191], v[48:51]
	v_mfma_f32_16x16x32_bf16 v[32:35], v[144:147], v[192:195], v[32:35]
	v_mfma_f32_16x16x32_bf16 v[32:35], v[148:151], v[196:199], v[32:35]
	v_mfma_f32_16x16x32_bf16 v[16:19], v[144:147], v[200:203], v[16:19]
	v_mfma_f32_16x16x32_bf16 v[16:19], v[148:151], v[204:207], v[16:19]
	v_mfma_f32_16x16x32_bf16 v[60:63], v[152:155], v[176:179], v[60:63]
	v_mfma_f32_16x16x32_bf16 v[60:63], v[156:159], v[180:183], v[60:63]
	v_mfma_f32_16x16x32_bf16 v[44:47], v[152:155], v[184:187], v[44:47]
	v_mfma_f32_16x16x32_bf16 v[44:47], v[156:159], v[188:191], v[44:47]
	v_mfma_f32_16x16x32_bf16 v[28:31], v[152:155], v[192:195], v[28:31]
	v_mfma_f32_16x16x32_bf16 v[28:31], v[156:159], v[196:199], v[28:31]
	v_mfma_f32_16x16x32_bf16 v[12:15], v[152:155], v[200:203], v[12:15]
	v_mfma_f32_16x16x32_bf16 v[12:15], v[156:159], v[204:207], v[12:15]
	s_setprio 0
	s_setprio 1
	v_mfma_f32_16x16x32_bf16 v[56:59], v[160:163], v[176:179], v[56:59]
	v_mfma_f32_16x16x32_bf16 v[56:59], v[164:167], v[180:183], v[56:59]
	v_mfma_f32_16x16x32_bf16 v[40:43], v[160:163], v[184:187], v[40:43]
	v_mfma_f32_16x16x32_bf16 v[40:43], v[164:167], v[188:191], v[40:43]
	v_mfma_f32_16x16x32_bf16 v[24:27], v[160:163], v[192:195], v[24:27]
	v_mfma_f32_16x16x32_bf16 v[24:27], v[164:167], v[196:199], v[24:27]
	v_mfma_f32_16x16x32_bf16 v[8:11], v[160:163], v[200:203], v[8:11]
	v_mfma_f32_16x16x32_bf16 v[8:11], v[164:167], v[204:207], v[8:11]
	v_mfma_f32_16x16x32_bf16 v[52:55], v[168:171], v[176:179], v[52:55]
	v_mfma_f32_16x16x32_bf16 v[52:55], v[172:175], v[180:183], v[52:55]
	v_mfma_f32_16x16x32_bf16 v[36:39], v[168:171], v[184:187], v[36:39]
	v_mfma_f32_16x16x32_bf16 v[36:39], v[172:175], v[188:191], v[36:39]
	v_mfma_f32_16x16x32_bf16 v[20:23], v[168:171], v[192:195], v[20:23]
	v_mfma_f32_16x16x32_bf16 v[20:23], v[172:175], v[196:199], v[20:23]
	v_mfma_f32_16x16x32_bf16 v[4:7], v[168:171], v[200:203], v[4:7]
	v_mfma_f32_16x16x32_bf16 v[4:7], v[172:175], v[204:207], v[4:7]
	s_setprio 0
	s_barrier
	s_add_i32 s43, s43, 2
	s_add_u32 s6, s6, 0x100
	s_addc_u32 s7, s7, 0
	s_cmp_gt_u32 s43, 29
	s_cbranch_scc0 .LBB0_1516
	s_cmpk_lt_u32 s21, 0x100
	s_cbranch_scc0 .LBB0_1519
	s_barrier

.LBB0_1876:
	v_add_u32_e32 v2, s83, v144
	ds_read_b128 v[146:149], v2
	ds_read_b128 v[150:153], v2 offset:1024
	ds_read_b128 v[154:157], v2 offset:2048
	ds_read_b128 v[158:161], v2 offset:3072
	v_add_u32_e32 v2, s44, v144
	ds_read_b128 v[162:165], v2
	ds_read_b128 v[166:169], v2 offset:1024
	ds_read_b128 v[170:173], v2 offset:2048
	ds_read_b128 v[174:177], v2 offset:3072
	s_add_i32 s70, s18, 2
	s_add_u32 s71, s42, 0x80
	s_addc_u32 s19, s43, 0
	s_cmp_eq_u32 s57, s18
	s_cselect_b32 s18, s34, s71
	s_cselect_b32 s19, s35, s19
	s_cselect_b32 s77, s25, s69
	s_cselect_b32 s76, s24, s68
	v_lshl_add_u64 v[210:211], s[42:43], 0, v[140:141]
	s_add_i32 m0, s23, 0xc000
	ds_read_b128 v[178:181], v145
	ds_read_b128 v[182:185], v145 offset:1024
	ds_read_b128 v[186:189], v145 offset:2048
	ds_read_b128 v[190:193], v145 offset:3072
	ds_read_b128 v[194:197], v145 offset:4096
	ds_read_b128 v[198:201], v145 offset:5120
	ds_read_b128 v[202:205], v145 offset:6144
	ds_read_b128 v[206:209], v145 offset:7168
	global_load_lds_dwordx4 v[210:211], off
	v_lshl_add_u64 v[210:211], s[42:43], 0, v[142:143]
	s_add_i32 m0, s23, 0xe000
	s_nop 0
	global_load_lds_dwordx4 v[210:211], off
	s_waitcnt vmcnt(8)
	s_waitcnt lgkmcnt(0)
	s_barrier
	s_setprio 1
	s_waitcnt lgkmcnt(0)
	v_mfma_f32_16x16x32_bf16 v[120:123], v[146:149], v[178:181], v[120:123]
	v_mfma_f32_16x16x32_bf16 v[120:123], v[150:153], v[182:185], v[120:123]
	v_mfma_f32_16x16x32_bf16 v[112:115], v[146:149], v[186:189], v[112:115]
	v_mfma_f32_16x16x32_bf16 v[112:115], v[150:153], v[190:193], v[112:115]
	v_mfma_f32_16x16x32_bf16 v[96:99], v[146:149], v[194:197], v[96:99]
	v_mfma_f32_16x16x32_bf16 v[96:99], v[150:153], v[198:201], v[96:99]
	v_mfma_f32_16x16x32_bf16 v[80:83], v[146:149], v[202:205], v[80:83]
	v_mfma_f32_16x16x32_bf16 v[80:83], v[150:153], v[206:209], v[80:83]
	v_mfma_f32_16x16x32_bf16 v[128:131], v[154:157], v[178:181], v[128:131]
	v_mfma_f32_16x16x32_bf16 v[128:131], v[158:161], v[182:185], v[128:131]
	v_mfma_f32_16x16x32_bf16 v[108:111], v[154:157], v[186:189], v[108:111]
	v_mfma_f32_16x16x32_bf16 v[108:111], v[158:161], v[190:193], v[108:111]
	v_mfma_f32_16x16x32_bf16 v[92:95], v[154:157], v[194:197], v[92:95]
	v_mfma_f32_16x16x32_bf16 v[92:95], v[158:161], v[198:201], v[92:95]
	v_mfma_f32_16x16x32_bf16 v[76:79], v[154:157], v[202:205], v[76:79]
	v_mfma_f32_16x16x32_bf16 v[76:79], v[158:161], v[206:209], v[76:79]
	s_setprio 0
	s_setprio 1
	v_mfma_f32_16x16x32_bf16 v[124:127], v[162:165], v[178:181], v[124:127]
	v_mfma_f32_16x16x32_bf16 v[124:127], v[166:169], v[182:185], v[124:127]
	v_mfma_f32_16x16x32_bf16 v[104:107], v[162:165], v[186:189], v[104:107]
	v_mfma_f32_16x16x32_bf16 v[104:107], v[166:169], v[190:193], v[104:107]
	v_mfma_f32_16x16x32_bf16 v[88:91], v[162:165], v[194:197], v[88:91]
	v_mfma_f32_16x16x32_bf16 v[88:91], v[166:169], v[198:201], v[88:91]
	v_mfma_f32_16x16x32_bf16 v[72:75], v[162:165], v[202:205], v[72:75]
	v_mfma_f32_16x16x32_bf16 v[72:75], v[166:169], v[206:209], v[72:75]
	v_mfma_f32_16x16x32_bf16 v[116:119], v[170:173], v[178:181], v[116:119]
	v_mfma_f32_16x16x32_bf16 v[116:119], v[174:177], v[182:185], v[116:119]
	v_mfma_f32_16x16x32_bf16 v[100:103], v[170:173], v[186:189], v[100:103]
	v_mfma_f32_16x16x32_bf16 v[100:103], v[174:177], v[190:193], v[100:103]
	v_mfma_f32_16x16x32_bf16 v[84:87], v[170:173], v[194:197], v[84:87]
	v_mfma_f32_16x16x32_bf16 v[84:87], v[174:177], v[198:201], v[84:87]
	v_mfma_f32_16x16x32_bf16 v[68:71], v[170:173], v[202:205], v[68:71]
	v_mfma_f32_16x16x32_bf16 v[68:71], v[174:177], v[206:209], v[68:71]
	s_setprio 0
	s_barrier
	s_mov_b32 m0, s16
	v_lshl_add_u64 v[210:211], s[76:77], 0, v[134:135]
	v_lshl_add_u64 v[216:217], s[76:77], 0, v[138:139]
	s_add_u32 s76, s76, s4
	ds_read_b128 v[178:181], v145 offset:16384
	ds_read_b128 v[182:185], v145 offset:17408
	ds_read_b128 v[186:189], v145 offset:18432
	ds_read_b128 v[190:193], v145 offset:19456
	ds_read_b128 v[194:197], v145 offset:20480
	ds_read_b128 v[198:201], v145 offset:21504
	ds_read_b128 v[202:205], v145 offset:22528
	ds_read_b128 v[206:209], v145 offset:23552
	global_load_lds_dwordx4 v[210:211], off
	s_mov_b32 m0, s20
	s_addc_u32 s77, s77, s5
	global_load_lds_dwordx4 v[216:217], off
	v_lshl_add_u64 v[218:219], s[76:77], 0, v[134:135]
	s_mov_b32 m0, s21
	v_lshl_add_u64 v[220:221], s[76:77], 0, v[138:139]
	global_load_lds_dwordx4 v[218:219], off
	s_mov_b32 m0, s22
	v_lshl_add_u64 v[222:223], s[18:19], 0, v[132:133]
	global_load_lds_dwordx4 v[220:221], off
	s_mov_b32 m0, s23
	v_lshl_add_u64 v[224:225], s[18:19], 0, v[136:137]
	global_load_lds_dwordx4 v[222:223], off
	s_mov_b32 m0, s26
	s_nop 0
	global_load_lds_dwordx4 v[224:225], off
	s_waitcnt vmcnt(8)
	s_waitcnt lgkmcnt(0)
	s_barrier
	s_setprio 1
	s_waitcnt lgkmcnt(0)
	v_mfma_f32_16x16x32_bf16 v[64:67], v[146:149], v[178:181], v[64:67]
	v_mfma_f32_16x16x32_bf16 v[64:67], v[150:153], v[182:185], v[64:67]
	v_mfma_f32_16x16x32_bf16 v[48:51], v[146:149], v[186:189], v[48:51]
	v_mfma_f32_16x16x32_bf16 v[48:51], v[150:153], v[190:193], v[48:51]
	v_mfma_f32_16x16x32_bf16 v[32:35], v[146:149], v[194:197], v[32:35]
	v_mfma_f32_16x16x32_bf16 v[32:35], v[150:153], v[198:201], v[32:35]
	v_mfma_f32_16x16x32_bf16 v[16:19], v[146:149], v[202:205], v[16:19]
	v_mfma_f32_16x16x32_bf16 v[16:19], v[150:153], v[206:209], v[16:19]
	v_mfma_f32_16x16x32_bf16 v[60:63], v[154:157], v[178:181], v[60:63]
	v_mfma_f32_16x16x32_bf16 v[60:63], v[158:161], v[182:185], v[60:63]
	v_mfma_f32_16x16x32_bf16 v[44:47], v[154:157], v[186:189], v[44:47]
	v_mfma_f32_16x16x32_bf16 v[44:47], v[158:161], v[190:193], v[44:47]
	v_mfma_f32_16x16x32_bf16 v[28:31], v[154:157], v[194:197], v[28:31]
	v_mfma_f32_16x16x32_bf16 v[28:31], v[158:161], v[198:201], v[28:31]
	v_mfma_f32_16x16x32_bf16 v[12:15], v[154:157], v[202:205], v[12:15]
	v_mfma_f32_16x16x32_bf16 v[12:15], v[158:161], v[206:209], v[12:15]
	s_setprio 0
	s_setprio 1
	v_mfma_f32_16x16x32_bf16 v[56:59], v[162:165], v[178:181], v[56:59]
	v_mfma_f32_16x16x32_bf16 v[56:59], v[166:169], v[182:185], v[56:59]
	v_mfma_f32_16x16x32_bf16 v[40:43], v[162:165], v[186:189], v[40:43]
	v_mfma_f32_16x16x32_bf16 v[40:43], v[166:169], v[190:193], v[40:43]
	v_mfma_f32_16x16x32_bf16 v[24:27], v[162:165], v[194:197], v[24:27]
	v_mfma_f32_16x16x32_bf16 v[24:27], v[166:169], v[198:201], v[24:27]
	v_mfma_f32_16x16x32_bf16 v[8:11], v[162:165], v[202:205], v[8:11]
	v_mfma_f32_16x16x32_bf16 v[8:11], v[166:169], v[206:209], v[8:11]
	v_mfma_f32_16x16x32_bf16 v[52:55], v[170:173], v[178:181], v[52:55]
	v_mfma_f32_16x16x32_bf16 v[52:55], v[174:177], v[182:185], v[52:55]
	v_mfma_f32_16x16x32_bf16 v[36:39], v[170:173], v[186:189], v[36:39]
	v_mfma_f32_16x16x32_bf16 v[36:39], v[174:177], v[190:193], v[36:39]
	v_mfma_f32_16x16x32_bf16 v[20:23], v[170:173], v[194:197], v[20:23]
	v_mfma_f32_16x16x32_bf16 v[20:23], v[174:177], v[198:201], v[20:23]
	v_mfma_f32_16x16x32_bf16 v[4:7], v[170:173], v[202:205], v[4:7]
	v_mfma_f32_16x16x32_bf16 v[4:7], v[174:177], v[206:209], v[4:7]
	s_setprio 0
	s_barrier
	v_add_u32_e32 v2, s45, v144
	ds_read_b128 v[146:149], v2
	ds_read_b128 v[150:153], v2 offset:1024
	ds_read_b128 v[154:157], v2 offset:2048
	ds_read_b128 v[158:161], v2 offset:3072
	v_add_u32_e32 v2, s74, v144
	ds_read_b128 v[162:165], v2
	ds_read_b128 v[166:169], v2 offset:1024
	ds_read_b128 v[170:173], v2 offset:2048
	ds_read_b128 v[174:177], v2 offset:3072
	s_add_u32 s18, s18, s4
	s_addc_u32 s19, s19, s5
	s_mov_b32 m0, s27
	v_lshl_add_u64 v[226:227], s[18:19], 0, v[132:133]
	ds_read_b128 v[178:181], v145 offset:32768
	ds_read_b128 v[182:185], v145 offset:33792
	ds_read_b128 v[186:189], v145 offset:34816
	ds_read_b128 v[190:193], v145 offset:35840
	ds_read_b128 v[194:197], v145 offset:36864
	ds_read_b128 v[198:201], v145 offset:37888
	ds_read_b128 v[202:205], v145 offset:38912
	ds_read_b128 v[206:209], v145 offset:39936
	global_load_lds_dwordx4 v[226:227], off
	v_lshl_add_u64 v[226:227], s[18:19], 0, v[136:137]
	s_mov_b32 m0, s37
	s_nop 0
	global_load_lds_dwordx4 v[226:227], off
	s_waitcnt vmcnt(8)
	s_waitcnt lgkmcnt(0)
	s_barrier
	s_setprio 1
	s_waitcnt lgkmcnt(0)
	v_mfma_f32_16x16x32_bf16 v[120:123], v[146:149], v[178:181], v[120:123]
	v_mfma_f32_16x16x32_bf16 v[120:123], v[150:153], v[182:185], v[120:123]
	v_mfma_f32_16x16x32_bf16 v[112:115], v[146:149], v[186:189], v[112:115]
	v_mfma_f32_16x16x32_bf16 v[112:115], v[150:153], v[190:193], v[112:115]
	v_mfma_f32_16x16x32_bf16 v[96:99], v[146:149], v[194:197], v[96:99]
	v_mfma_f32_16x16x32_bf16 v[96:99], v[150:153], v[198:201], v[96:99]
	v_mfma_f32_16x16x32_bf16 v[80:83], v[146:149], v[202:205], v[80:83]
	v_mfma_f32_16x16x32_bf16 v[80:83], v[150:153], v[206:209], v[80:83]
	v_mfma_f32_16x16x32_bf16 v[128:131], v[154:157], v[178:181], v[128:131]
	v_mfma_f32_16x16x32_bf16 v[128:131], v[158:161], v[182:185], v[128:131]
	v_mfma_f32_16x16x32_bf16 v[108:111], v[154:157], v[186:189], v[108:111]
	v_mfma_f32_16x16x32_bf16 v[108:111], v[158:161], v[190:193], v[108:111]
	v_mfma_f32_16x16x32_bf16 v[92:95], v[154:157], v[194:197], v[92:95]
	v_mfma_f32_16x16x32_bf16 v[92:95], v[158:161], v[198:201], v[92:95]
	v_mfma_f32_16x16x32_bf16 v[76:79], v[154:157], v[202:205], v[76:79]
	v_mfma_f32_16x16x32_bf16 v[76:79], v[158:161], v[206:209], v[76:79]
	s_setprio 0
	s_setprio 1
	v_mfma_f32_16x16x32_bf16 v[124:127], v[162:165], v[178:181], v[124:127]
	v_mfma_f32_16x16x32_bf16 v[124:127], v[166:169], v[182:185], v[124:127]
	v_mfma_f32_16x16x32_bf16 v[104:107], v[162:165], v[186:189], v[104:107]
	v_mfma_f32_16x16x32_bf16 v[104:107], v[166:169], v[190:193], v[104:107]
	v_mfma_f32_16x16x32_bf16 v[88:91], v[162:165], v[194:197], v[88:91]
	v_mfma_f32_16x16x32_bf16 v[88:91], v[166:169], v[198:201], v[88:91]
	v_mfma_f32_16x16x32_bf16 v[72:75], v[162:165], v[202:205], v[72:75]
	v_mfma_f32_16x16x32_bf16 v[72:75], v[166:169], v[206:209], v[72:75]
	v_mfma_f32_16x16x32_bf16 v[116:119], v[170:173], v[178:181], v[116:119]
	v_mfma_f32_16x16x32_bf16 v[116:119], v[174:177], v[182:185], v[116:119]
	v_mfma_f32_16x16x32_bf16 v[100:103], v[170:173], v[186:189], v[100:103]
	v_mfma_f32_16x16x32_bf16 v[100:103], v[174:177], v[190:193], v[100:103]
	v_mfma_f32_16x16x32_bf16 v[84:87], v[170:173], v[194:197], v[84:87]
	v_mfma_f32_16x16x32_bf16 v[84:87], v[174:177], v[198:201], v[84:87]
	v_mfma_f32_16x16x32_bf16 v[68:71], v[170:173], v[202:205], v[68:71]
	v_mfma_f32_16x16x32_bf16 v[68:71], v[174:177], v[206:209], v[68:71]
	s_setprio 0
	s_barrier
	s_mov_b32 m0, s49
	v_lshl_add_u64 v[210:211], v[210:211], 0, s[64:65]
	ds_read_b128 v[178:181], v145 offset:49152
	ds_read_b128 v[182:185], v145 offset:50176
	ds_read_b128 v[186:189], v145 offset:51200
	ds_read_b128 v[190:193], v145 offset:52224
	ds_read_b128 v[194:197], v145 offset:53248
	ds_read_b128 v[198:201], v145 offset:54272
	ds_read_b128 v[202:205], v145 offset:55296
	ds_read_b128 v[206:209], v145 offset:56320
	global_load_lds_dwordx4 v[210:211], off
	v_lshl_add_u64 v[210:211], v[216:217], 0, s[64:65]
	s_mov_b32 m0, s50
	s_nop 0
	global_load_lds_dwordx4 v[210:211], off
	v_lshl_add_u64 v[210:211], v[218:219], 0, s[64:65]
	s_mov_b32 m0, s53
	s_nop 0
	global_load_lds_dwordx4 v[210:211], off
	v_lshl_add_u64 v[210:211], v[220:221], 0, s[64:65]
	s_mov_b32 m0, s56
	s_nop 0
	global_load_lds_dwordx4 v[210:211], off
	v_lshl_add_u64 v[210:211], v[222:223], 0, s[64:65]
	s_mov_b32 m0, s51
	s_nop 0
	global_load_lds_dwordx4 v[210:211], off
	v_lshl_add_u64 v[210:211], v[224:225], 0, s[64:65]
	s_mov_b32 m0, s52
	s_nop 0
	global_load_lds_dwordx4 v[210:211], off
	s_waitcnt vmcnt(8)
	s_waitcnt lgkmcnt(0)
	s_barrier
	s_setprio 1
	s_waitcnt lgkmcnt(0)
	v_mfma_f32_16x16x32_bf16 v[64:67], v[146:149], v[178:181], v[64:67]
	v_mfma_f32_16x16x32_bf16 v[64:67], v[150:153], v[182:185], v[64:67]
	v_mfma_f32_16x16x32_bf16 v[48:51], v[146:149], v[186:189], v[48:51]
	v_mfma_f32_16x16x32_bf16 v[48:51], v[150:153], v[190:193], v[48:51]
	v_mfma_f32_16x16x32_bf16 v[32:35], v[146:149], v[194:197], v[32:35]
	v_mfma_f32_16x16x32_bf16 v[32:35], v[150:153], v[198:201], v[32:35]
	v_mfma_f32_16x16x32_bf16 v[16:19], v[146:149], v[202:205], v[16:19]
	v_mfma_f32_16x16x32_bf16 v[16:19], v[150:153], v[206:209], v[16:19]
	v_mfma_f32_16x16x32_bf16 v[60:63], v[154:157], v[178:181], v[60:63]
	v_mfma_f32_16x16x32_bf16 v[60:63], v[158:161], v[182:185], v[60:63]
	v_mfma_f32_16x16x32_bf16 v[44:47], v[154:157], v[186:189], v[44:47]
	v_mfma_f32_16x16x32_bf16 v[44:47], v[158:161], v[190:193], v[44:47]
	v_mfma_f32_16x16x32_bf16 v[28:31], v[154:157], v[194:197], v[28:31]
	v_mfma_f32_16x16x32_bf16 v[28:31], v[158:161], v[198:201], v[28:31]
	v_mfma_f32_16x16x32_bf16 v[12:15], v[154:157], v[202:205], v[12:15]
	v_mfma_f32_16x16x32_bf16 v[12:15], v[158:161], v[206:209], v[12:15]
	s_setprio 0
	s_setprio 1
	v_mfma_f32_16x16x32_bf16 v[56:59], v[162:165], v[178:181], v[56:59]
	v_mfma_f32_16x16x32_bf16 v[56:59], v[166:169], v[182:185], v[56:59]
	v_mfma_f32_16x16x32_bf16 v[40:43], v[162:165], v[186:189], v[40:43]
	v_mfma_f32_16x16x32_bf16 v[40:43], v[166:169], v[190:193], v[40:43]
	v_mfma_f32_16x16x32_bf16 v[24:27], v[162:165], v[194:197], v[24:27]
	v_mfma_f32_16x16x32_bf16 v[24:27], v[166:169], v[198:201], v[24:27]
	v_mfma_f32_16x16x32_bf16 v[8:11], v[162:165], v[202:205], v[8:11]
	v_mfma_f32_16x16x32_bf16 v[8:11], v[166:169], v[206:209], v[8:11]
	v_mfma_f32_16x16x32_bf16 v[52:55], v[170:173], v[178:181], v[52:55]
	v_mfma_f32_16x16x32_bf16 v[52:55], v[174:177], v[182:185], v[52:55]
	v_mfma_f32_16x16x32_bf16 v[36:39], v[170:173], v[186:189], v[36:39]
	v_mfma_f32_16x16x32_bf16 v[36:39], v[174:177], v[190:193], v[36:39]
	v_mfma_f32_16x16x32_bf16 v[20:23], v[170:173], v[194:197], v[20:23]
	v_mfma_f32_16x16x32_bf16 v[20:23], v[174:177], v[198:201], v[20:23]
	v_mfma_f32_16x16x32_bf16 v[4:7], v[170:173], v[202:205], v[4:7]
	v_mfma_f32_16x16x32_bf16 v[4:7], v[174:177], v[206:209], v[4:7]
	s_setprio 0
	s_barrier
	s_add_u32 s42, s42, 0x100
	s_addc_u32 s43, s43, 0
	s_add_u32 s68, s68, 0x100
	s_addc_u32 s69, s69, 0
	s_cmp_ge_i32 s70, s46
	s_mov_b32 s18, s70
	s_cbranch_scc0 .LBB0_1876

.LBB0_2329:
	s_add_i32 s43, s12, 2
	v_add_u32_e32 v156, s83, v142
	v_add_u32_e32 v172, s44, v142
	s_add_u32 s10, s8, 0x100
	ds_read_b128 v[144:147], v156
	ds_read_b128 v[148:151], v156 offset:1024
	ds_read_b128 v[152:155], v156 offset:2048
	ds_read_b128 v[156:159], v156 offset:3072
	ds_read_b128 v[160:163], v172
	ds_read_b128 v[164:167], v172 offset:1024
	ds_read_b128 v[168:171], v172 offset:2048
	ds_read_b128 v[172:175], v172 offset:3072
	s_addc_u32 s11, s9, 0
	s_cmp_lg_u32 s42, s12
	s_cselect_b32 s46, s10, 0
	s_cselect_b32 s47, s11, 0
	s_add_u32 s12, s6, s46
	s_addc_u32 s13, s7, s47
	s_add_u32 s46, s4, s46
	s_addc_u32 s47, s5, s47
	v_lshl_add_u64 v[208:209], v[138:139], 0, s[8:9]
	s_add_i32 m0, s22, 0xc000
	ds_read_b128 v[176:179], v143
	ds_read_b128 v[180:183], v143 offset:1024
	ds_read_b128 v[184:187], v143 offset:2048
	ds_read_b128 v[188:191], v143 offset:3072
	ds_read_b128 v[192:195], v143 offset:4096
	ds_read_b128 v[196:199], v143 offset:5120
	ds_read_b128 v[200:203], v143 offset:6144
	ds_read_b128 v[204:207], v143 offset:7168
	global_load_lds_dwordx4 v[208:209], off
	v_lshl_add_u64 v[208:209], v[140:141], 0, s[8:9]
	s_add_i32 m0, s22, 0xe000
	s_nop 0
	global_load_lds_dwordx4 v[208:209], off
	s_waitcnt vmcnt(8)
	s_waitcnt lgkmcnt(0)
	s_barrier
	s_setprio 1
	s_waitcnt lgkmcnt(0)
	v_mfma_f32_16x16x32_bf16 v[124:127], v[144:147], v[176:179], v[124:127]
	v_mfma_f32_16x16x32_bf16 v[124:127], v[148:151], v[180:183], v[124:127]
	v_mfma_f32_16x16x32_bf16 v[112:115], v[144:147], v[184:187], v[112:115]
	v_mfma_f32_16x16x32_bf16 v[112:115], v[148:151], v[188:191], v[112:115]
	v_mfma_f32_16x16x32_bf16 v[96:99], v[144:147], v[192:195], v[96:99]
	v_mfma_f32_16x16x32_bf16 v[96:99], v[148:151], v[196:199], v[96:99]
	v_mfma_f32_16x16x32_bf16 v[80:83], v[144:147], v[200:203], v[80:83]
	v_mfma_f32_16x16x32_bf16 v[80:83], v[148:151], v[204:207], v[80:83]
	v_mfma_f32_16x16x32_bf16 v[128:131], v[152:155], v[176:179], v[128:131]
	v_mfma_f32_16x16x32_bf16 v[128:131], v[156:159], v[180:183], v[128:131]
	v_mfma_f32_16x16x32_bf16 v[108:111], v[152:155], v[184:187], v[108:111]
	v_mfma_f32_16x16x32_bf16 v[108:111], v[156:159], v[188:191], v[108:111]
	v_mfma_f32_16x16x32_bf16 v[92:95], v[152:155], v[192:195], v[92:95]
	v_mfma_f32_16x16x32_bf16 v[92:95], v[156:159], v[196:199], v[92:95]
	v_mfma_f32_16x16x32_bf16 v[76:79], v[152:155], v[200:203], v[76:79]
	v_mfma_f32_16x16x32_bf16 v[76:79], v[156:159], v[204:207], v[76:79]
	s_setprio 0
	s_setprio 1
	v_mfma_f32_16x16x32_bf16 v[120:123], v[160:163], v[176:179], v[120:123]
	v_mfma_f32_16x16x32_bf16 v[120:123], v[164:167], v[180:183], v[120:123]
	v_mfma_f32_16x16x32_bf16 v[104:107], v[160:163], v[184:187], v[104:107]
	v_mfma_f32_16x16x32_bf16 v[104:107], v[164:167], v[188:191], v[104:107]
	v_mfma_f32_16x16x32_bf16 v[88:91], v[160:163], v[192:195], v[88:91]
	v_mfma_f32_16x16x32_bf16 v[88:91], v[164:167], v[196:199], v[88:91]
	v_mfma_f32_16x16x32_bf16 v[72:75], v[160:163], v[200:203], v[72:75]
	v_mfma_f32_16x16x32_bf16 v[72:75], v[164:167], v[204:207], v[72:75]
	v_mfma_f32_16x16x32_bf16 v[116:119], v[168:171], v[176:179], v[116:119]
	v_mfma_f32_16x16x32_bf16 v[116:119], v[172:175], v[180:183], v[116:119]
	v_mfma_f32_16x16x32_bf16 v[100:103], v[168:171], v[184:187], v[100:103]
	v_mfma_f32_16x16x32_bf16 v[100:103], v[172:175], v[188:191], v[100:103]
	v_mfma_f32_16x16x32_bf16 v[84:87], v[168:171], v[192:195], v[84:87]
	v_mfma_f32_16x16x32_bf16 v[84:87], v[172:175], v[196:199], v[84:87]
	v_mfma_f32_16x16x32_bf16 v[68:71], v[168:171], v[200:203], v[68:71]
	v_mfma_f32_16x16x32_bf16 v[68:71], v[172:175], v[204:207], v[68:71]
	s_setprio 0
	s_barrier
	s_mov_b32 m0, s18
	v_lshl_add_u64 v[208:209], s[46:47], 0, v[2:3]
	s_add_u32 s8, s46, s2
	ds_read_b128 v[176:179], v143 offset:16384
	ds_read_b128 v[180:183], v143 offset:17408
	ds_read_b128 v[184:187], v143 offset:18432
	ds_read_b128 v[188:191], v143 offset:19456
	ds_read_b128 v[192:195], v143 offset:20480
	ds_read_b128 v[196:199], v143 offset:21504
	ds_read_b128 v[200:203], v143 offset:22528
	ds_read_b128 v[204:207], v143 offset:23552
	global_load_lds_dwordx4 v[208:209], off
	v_lshl_add_u64 v[210:211], s[46:47], 0, v[136:137]
	s_mov_b32 m0, s19
	s_addc_u32 s9, s47, s3
	global_load_lds_dwordx4 v[210:211], off
	v_lshl_add_u64 v[216:217], s[8:9], 0, v[2:3]
	s_mov_b32 m0, s20
	v_lshl_add_u64 v[218:219], s[8:9], 0, v[136:137]
	global_load_lds_dwordx4 v[216:217], off
	s_mov_b32 m0, s21
	v_lshl_add_u64 v[220:221], s[12:13], 0, v[132:133]
	global_load_lds_dwordx4 v[218:219], off
	s_mov_b32 m0, s22
	v_lshl_add_u64 v[222:223], s[12:13], 0, v[134:135]
	global_load_lds_dwordx4 v[220:221], off
	s_mov_b32 m0, s23
	s_nop 0
	global_load_lds_dwordx4 v[222:223], off
	s_waitcnt vmcnt(8)
	s_waitcnt lgkmcnt(0)
	s_barrier
	s_setprio 1
	s_waitcnt lgkmcnt(0)
	v_mfma_f32_16x16x32_bf16 v[64:67], v[144:147], v[176:179], v[64:67]
	v_mfma_f32_16x16x32_bf16 v[64:67], v[148:151], v[180:183], v[64:67]
	v_mfma_f32_16x16x32_bf16 v[48:51], v[144:147], v[184:187], v[48:51]
	v_mfma_f32_16x16x32_bf16 v[48:51], v[148:151], v[188:191], v[48:51]
	v_mfma_f32_16x16x32_bf16 v[32:35], v[144:147], v[192:195], v[32:35]
	v_mfma_f32_16x16x32_bf16 v[32:35], v[148:151], v[196:199], v[32:35]
	v_mfma_f32_16x16x32_bf16 v[16:19], v[144:147], v[200:203], v[16:19]
	v_mfma_f32_16x16x32_bf16 v[16:19], v[148:151], v[204:207], v[16:19]
	v_mfma_f32_16x16x32_bf16 v[60:63], v[152:155], v[176:179], v[60:63]
	v_mfma_f32_16x16x32_bf16 v[60:63], v[156:159], v[180:183], v[60:63]
	v_mfma_f32_16x16x32_bf16 v[44:47], v[152:155], v[184:187], v[44:47]
	v_mfma_f32_16x16x32_bf16 v[44:47], v[156:159], v[188:191], v[44:47]
	v_mfma_f32_16x16x32_bf16 v[28:31], v[152:155], v[192:195], v[28:31]
	v_mfma_f32_16x16x32_bf16 v[28:31], v[156:159], v[196:199], v[28:31]
	v_mfma_f32_16x16x32_bf16 v[12:15], v[152:155], v[200:203], v[12:15]
	v_mfma_f32_16x16x32_bf16 v[12:15], v[156:159], v[204:207], v[12:15]
	s_setprio 0
	s_setprio 1
	v_mfma_f32_16x16x32_bf16 v[56:59], v[160:163], v[176:179], v[56:59]
	v_mfma_f32_16x16x32_bf16 v[56:59], v[164:167], v[180:183], v[56:59]
	v_mfma_f32_16x16x32_bf16 v[40:43], v[160:163], v[184:187], v[40:43]
	v_mfma_f32_16x16x32_bf16 v[40:43], v[164:167], v[188:191], v[40:43]
	v_mfma_f32_16x16x32_bf16 v[24:27], v[160:163], v[192:195], v[24:27]
	v_mfma_f32_16x16x32_bf16 v[24:27], v[164:167], v[196:199], v[24:27]
	v_mfma_f32_16x16x32_bf16 v[8:11], v[160:163], v[200:203], v[8:11]
	v_mfma_f32_16x16x32_bf16 v[8:11], v[164:167], v[204:207], v[8:11]
	v_mfma_f32_16x16x32_bf16 v[52:55], v[168:171], v[176:179], v[52:55]
	v_mfma_f32_16x16x32_bf16 v[52:55], v[172:175], v[180:183], v[52:55]
	v_mfma_f32_16x16x32_bf16 v[36:39], v[168:171], v[184:187], v[36:39]
	v_mfma_f32_16x16x32_bf16 v[36:39], v[172:175], v[188:191], v[36:39]
	v_mfma_f32_16x16x32_bf16 v[20:23], v[168:171], v[192:195], v[20:23]
	v_mfma_f32_16x16x32_bf16 v[20:23], v[172:175], v[196:199], v[20:23]
	v_mfma_f32_16x16x32_bf16 v[4:7], v[168:171], v[200:203], v[4:7]
	v_mfma_f32_16x16x32_bf16 v[4:7], v[172:175], v[204:207], v[4:7]
	s_setprio 0
	s_barrier
	v_add_u32_e32 v156, s45, v142
	v_add_u32_e32 v172, s74, v142
	ds_read_b128 v[144:147], v156
	ds_read_b128 v[148:151], v156 offset:1024
	ds_read_b128 v[152:155], v156 offset:2048
	ds_read_b128 v[156:159], v156 offset:3072
	ds_read_b128 v[160:163], v172
	ds_read_b128 v[164:167], v172 offset:1024
	ds_read_b128 v[168:171], v172 offset:2048
	ds_read_b128 v[172:175], v172 offset:3072
	s_add_u32 s8, s12, s2
	s_addc_u32 s9, s13, s3
	s_mov_b32 m0, s24
	v_lshl_add_u64 v[224:225], s[8:9], 0, v[132:133]
	ds_read_b128 v[176:179], v143 offset:32768
	ds_read_b128 v[180:183], v143 offset:33792
	ds_read_b128 v[184:187], v143 offset:34816
	ds_read_b128 v[188:191], v143 offset:35840
	ds_read_b128 v[192:195], v143 offset:36864
	ds_read_b128 v[196:199], v143 offset:37888
	ds_read_b128 v[200:203], v143 offset:38912
	ds_read_b128 v[204:207], v143 offset:39936
	global_load_lds_dwordx4 v[224:225], off
	v_lshl_add_u64 v[224:225], s[8:9], 0, v[134:135]
	s_mov_b32 m0, s25
	s_nop 0
	global_load_lds_dwordx4 v[224:225], off
	s_waitcnt vmcnt(8)
	s_waitcnt lgkmcnt(0)
	s_barrier
	s_setprio 1
	s_waitcnt lgkmcnt(0)
	v_mfma_f32_16x16x32_bf16 v[124:127], v[144:147], v[176:179], v[124:127]
	v_mfma_f32_16x16x32_bf16 v[124:127], v[148:151], v[180:183], v[124:127]
	v_mfma_f32_16x16x32_bf16 v[112:115], v[144:147], v[184:187], v[112:115]
	v_mfma_f32_16x16x32_bf16 v[112:115], v[148:151], v[188:191], v[112:115]
	v_mfma_f32_16x16x32_bf16 v[96:99], v[144:147], v[192:195], v[96:99]
	v_mfma_f32_16x16x32_bf16 v[96:99], v[148:151], v[196:199], v[96:99]
	v_mfma_f32_16x16x32_bf16 v[80:83], v[144:147], v[200:203], v[80:83]
	v_mfma_f32_16x16x32_bf16 v[80:83], v[148:151], v[204:207], v[80:83]
	v_mfma_f32_16x16x32_bf16 v[128:131], v[152:155], v[176:179], v[128:131]
	v_mfma_f32_16x16x32_bf16 v[128:131], v[156:159], v[180:183], v[128:131]
	v_mfma_f32_16x16x32_bf16 v[108:111], v[152:155], v[184:187], v[108:111]
	v_mfma_f32_16x16x32_bf16 v[108:111], v[156:159], v[188:191], v[108:111]
	v_mfma_f32_16x16x32_bf16 v[92:95], v[152:155], v[192:195], v[92:95]
	v_mfma_f32_16x16x32_bf16 v[92:95], v[156:159], v[196:199], v[92:95]
	v_mfma_f32_16x16x32_bf16 v[76:79], v[152:155], v[200:203], v[76:79]
	v_mfma_f32_16x16x32_bf16 v[76:79], v[156:159], v[204:207], v[76:79]
	s_setprio 0
	s_setprio 1
	v_mfma_f32_16x16x32_bf16 v[120:123], v[160:163], v[176:179], v[120:123]
	v_mfma_f32_16x16x32_bf16 v[120:123], v[164:167], v[180:183], v[120:123]
	v_mfma_f32_16x16x32_bf16 v[104:107], v[160:163], v[184:187], v[104:107]
	v_mfma_f32_16x16x32_bf16 v[104:107], v[164:167], v[188:191], v[104:107]
	v_mfma_f32_16x16x32_bf16 v[88:91], v[160:163], v[192:195], v[88:91]
	v_mfma_f32_16x16x32_bf16 v[88:91], v[164:167], v[196:199], v[88:91]
	v_mfma_f32_16x16x32_bf16 v[72:75], v[160:163], v[200:203], v[72:75]
	v_mfma_f32_16x16x32_bf16 v[72:75], v[164:167], v[204:207], v[72:75]
	v_mfma_f32_16x16x32_bf16 v[116:119], v[168:171], v[176:179], v[116:119]
	v_mfma_f32_16x16x32_bf16 v[116:119], v[172:175], v[180:183], v[116:119]
	v_mfma_f32_16x16x32_bf16 v[100:103], v[168:171], v[184:187], v[100:103]
	v_mfma_f32_16x16x32_bf16 v[100:103], v[172:175], v[188:191], v[100:103]
	v_mfma_f32_16x16x32_bf16 v[84:87], v[168:171], v[192:195], v[84:87]
	v_mfma_f32_16x16x32_bf16 v[84:87], v[172:175], v[196:199], v[84:87]
	v_mfma_f32_16x16x32_bf16 v[68:71], v[168:171], v[200:203], v[68:71]
	v_mfma_f32_16x16x32_bf16 v[68:71], v[172:175], v[204:207], v[68:71]
	s_setprio 0
	s_barrier
	s_mov_b32 m0, s26
	v_lshl_add_u64 v[208:209], v[208:209], 0, s[64:65]
	ds_read_b128 v[176:179], v143 offset:49152
	ds_read_b128 v[180:183], v143 offset:50176
	ds_read_b128 v[184:187], v143 offset:51200
	ds_read_b128 v[188:191], v143 offset:52224
	ds_read_b128 v[192:195], v143 offset:53248
	ds_read_b128 v[196:199], v143 offset:54272
	ds_read_b128 v[200:203], v143 offset:55296
	ds_read_b128 v[204:207], v143 offset:56320
	global_load_lds_dwordx4 v[208:209], off
	v_lshl_add_u64 v[208:209], v[210:211], 0, s[64:65]
	s_mov_b32 m0, s27
	s_nop 0
	global_load_lds_dwordx4 v[208:209], off
	v_lshl_add_u64 v[208:209], v[216:217], 0, s[64:65]
	s_mov_b32 m0, s37
	s_nop 0
	global_load_lds_dwordx4 v[208:209], off
	v_lshl_add_u64 v[208:209], v[218:219], 0, s[64:65]
	s_mov_b32 m0, s40
	s_nop 0
	global_load_lds_dwordx4 v[208:209], off
	v_lshl_add_u64 v[208:209], v[220:221], 0, s[64:65]
	s_mov_b32 m0, s34
	s_nop 0
	global_load_lds_dwordx4 v[208:209], off
	v_lshl_add_u64 v[208:209], v[222:223], 0, s[64:65]
	s_mov_b32 m0, s35
	s_nop 0
	global_load_lds_dwordx4 v[208:209], off
	s_waitcnt vmcnt(8)
	s_waitcnt lgkmcnt(0)
	s_barrier
	s_setprio 1
	s_waitcnt lgkmcnt(0)
	v_mfma_f32_16x16x32_bf16 v[64:67], v[144:147], v[176:179], v[64:67]
	v_mfma_f32_16x16x32_bf16 v[64:67], v[148:151], v[180:183], v[64:67]
	v_mfma_f32_16x16x32_bf16 v[48:51], v[144:147], v[184:187], v[48:51]
	v_mfma_f32_16x16x32_bf16 v[48:51], v[148:151], v[188:191], v[48:51]
	v_mfma_f32_16x16x32_bf16 v[32:35], v[144:147], v[192:195], v[32:35]
	v_mfma_f32_16x16x32_bf16 v[32:35], v[148:151], v[196:199], v[32:35]
	v_mfma_f32_16x16x32_bf16 v[16:19], v[144:147], v[200:203], v[16:19]
	v_mfma_f32_16x16x32_bf16 v[16:19], v[148:151], v[204:207], v[16:19]
	v_mfma_f32_16x16x32_bf16 v[60:63], v[152:155], v[176:179], v[60:63]
	v_mfma_f32_16x16x32_bf16 v[60:63], v[156:159], v[180:183], v[60:63]
	v_mfma_f32_16x16x32_bf16 v[44:47], v[152:155], v[184:187], v[44:47]
	v_mfma_f32_16x16x32_bf16 v[44:47], v[156:159], v[188:191], v[44:47]
	v_mfma_f32_16x16x32_bf16 v[28:31], v[152:155], v[192:195], v[28:31]
	v_mfma_f32_16x16x32_bf16 v[28:31], v[156:159], v[196:199], v[28:31]
	v_mfma_f32_16x16x32_bf16 v[12:15], v[152:155], v[200:203], v[12:15]
	v_mfma_f32_16x16x32_bf16 v[12:15], v[156:159], v[204:207], v[12:15]
	s_setprio 0
	s_setprio 1
	v_mfma_f32_16x16x32_bf16 v[56:59], v[160:163], v[176:179], v[56:59]
	v_mfma_f32_16x16x32_bf16 v[56:59], v[164:167], v[180:183], v[56:59]
	v_mfma_f32_16x16x32_bf16 v[40:43], v[160:163], v[184:187], v[40:43]
	v_mfma_f32_16x16x32_bf16 v[40:43], v[164:167], v[188:191], v[40:43]
	v_mfma_f32_16x16x32_bf16 v[24:27], v[160:163], v[192:195], v[24:27]
	v_mfma_f32_16x16x32_bf16 v[24:27], v[164:167], v[196:199], v[24:27]
	v_mfma_f32_16x16x32_bf16 v[8:11], v[160:163], v[200:203], v[8:11]
	v_mfma_f32_16x16x32_bf16 v[8:11], v[164:167], v[204:207], v[8:11]
	v_mfma_f32_16x16x32_bf16 v[52:55], v[168:171], v[176:179], v[52:55]
	v_mfma_f32_16x16x32_bf16 v[52:55], v[172:175], v[180:183], v[52:55]
	v_mfma_f32_16x16x32_bf16 v[36:39], v[168:171], v[184:187], v[36:39]
	v_mfma_f32_16x16x32_bf16 v[36:39], v[172:175], v[188:191], v[36:39]
	v_mfma_f32_16x16x32_bf16 v[20:23], v[168:171], v[192:195], v[20:23]
	v_mfma_f32_16x16x32_bf16 v[20:23], v[172:175], v[196:199], v[20:23]
	v_mfma_f32_16x16x32_bf16 v[4:7], v[168:171], v[200:203], v[4:7]
	v_mfma_f32_16x16x32_bf16 v[4:7], v[172:175], v[204:207], v[4:7]
	s_setprio 0
	s_barrier
	s_cmp_ge_i32 s43, s41
	s_mov_b64 s[8:9], s[10:11]
	s_mov_b32 s12, s43
	s_cbranch_scc0 .LBB0_2329

.LBB0_2896:
	v_add_u32_e32 v148, s18, v126
	v_add_u32_e32 v172, s19, v126
	s_add_u32 s12, s46, s8
	ds_read_b128 v[128:131], v148
	ds_read_b128 v[132:135], v148 offset:1024
	ds_read_b128 v[140:143], v148 offset:2048
	ds_read_b128 v[148:151], v148 offset:3072
	ds_read_b128 v[160:163], v172
	ds_read_b128 v[164:167], v172 offset:1024
	ds_read_b128 v[168:171], v172 offset:2048
	ds_read_b128 v[172:175], v172 offset:3072
	s_addc_u32 s13, s47, s9
	s_add_u32 s12, s12, 0x34400100
	s_addc_u32 s13, s13, 0
	s_add_u32 s16, s48, s8
	s_addc_u32 s51, s49, s9
	s_cmpk_eq_i32 s8, 0xf00
	s_cselect_b32 s15, s11, s13
	s_cselect_b32 s14, s10, s12
	s_cselect_b32 s13, s3, s51
	s_cselect_b32 s12, s2, s16
	v_lshl_add_u64 v[208:209], v[122:123], 0, s[8:9]
	s_add_i32 m0, s27, 0xc000
	ds_read_b128 v[176:179], v127
	ds_read_b128 v[180:183], v127 offset:1024
	ds_read_b128 v[184:187], v127 offset:2048
	ds_read_b128 v[188:191], v127 offset:3072
	ds_read_b128 v[192:195], v127 offset:4096
	ds_read_b128 v[196:199], v127 offset:5120
	ds_read_b128 v[200:203], v127 offset:6144
	ds_read_b128 v[204:207], v127 offset:7168
	global_load_lds_dwordx4 v[208:209], off
	v_lshl_add_u64 v[208:209], v[124:125], 0, s[8:9]
	s_add_i32 m0, s27, 0xe000
	s_nop 0
	global_load_lds_dwordx4 v[208:209], off
	s_waitcnt vmcnt(8)
	s_waitcnt lgkmcnt(0)
	s_barrier
	s_setprio 1
	s_waitcnt lgkmcnt(0)
	v_mfma_f32_16x16x32_bf16 v[156:159], v[128:131], v[176:179], v[156:159]
	v_mfma_f32_16x16x32_bf16 v[156:159], v[132:135], v[180:183], v[156:159]
	v_mfma_f32_16x16x32_bf16 v[112:115], v[128:131], v[184:187], v[112:115]
	v_mfma_f32_16x16x32_bf16 v[112:115], v[132:135], v[188:191], v[112:115]
	v_mfma_f32_16x16x32_bf16 v[96:99], v[128:131], v[192:195], v[96:99]
	v_mfma_f32_16x16x32_bf16 v[96:99], v[132:135], v[196:199], v[96:99]
	v_mfma_f32_16x16x32_bf16 v[80:83], v[128:131], v[200:203], v[80:83]
	v_mfma_f32_16x16x32_bf16 v[80:83], v[132:135], v[204:207], v[80:83]
	v_mfma_f32_16x16x32_bf16 v[152:155], v[140:143], v[176:179], v[152:155]
	v_mfma_f32_16x16x32_bf16 v[152:155], v[148:151], v[180:183], v[152:155]
	v_mfma_f32_16x16x32_bf16 v[108:111], v[140:143], v[184:187], v[108:111]
	v_mfma_f32_16x16x32_bf16 v[108:111], v[148:151], v[188:191], v[108:111]
	v_mfma_f32_16x16x32_bf16 v[92:95], v[140:143], v[192:195], v[92:95]
	v_mfma_f32_16x16x32_bf16 v[92:95], v[148:151], v[196:199], v[92:95]
	v_mfma_f32_16x16x32_bf16 v[76:79], v[140:143], v[200:203], v[76:79]
	v_mfma_f32_16x16x32_bf16 v[76:79], v[148:151], v[204:207], v[76:79]
	s_setprio 0
	s_setprio 1
	v_mfma_f32_16x16x32_bf16 v[144:147], v[160:163], v[176:179], v[144:147]
	v_mfma_f32_16x16x32_bf16 v[144:147], v[164:167], v[180:183], v[144:147]
	v_mfma_f32_16x16x32_bf16 v[104:107], v[160:163], v[184:187], v[104:107]
	v_mfma_f32_16x16x32_bf16 v[104:107], v[164:167], v[188:191], v[104:107]
	v_mfma_f32_16x16x32_bf16 v[88:91], v[160:163], v[192:195], v[88:91]
	v_mfma_f32_16x16x32_bf16 v[88:91], v[164:167], v[196:199], v[88:91]
	v_mfma_f32_16x16x32_bf16 v[72:75], v[160:163], v[200:203], v[72:75]
	v_mfma_f32_16x16x32_bf16 v[72:75], v[164:167], v[204:207], v[72:75]
	v_mfma_f32_16x16x32_bf16 v[136:139], v[168:171], v[176:179], v[136:139]
	v_mfma_f32_16x16x32_bf16 v[136:139], v[172:175], v[180:183], v[136:139]
	v_mfma_f32_16x16x32_bf16 v[100:103], v[168:171], v[184:187], v[100:103]
	v_mfma_f32_16x16x32_bf16 v[100:103], v[172:175], v[188:191], v[100:103]
	v_mfma_f32_16x16x32_bf16 v[84:87], v[168:171], v[192:195], v[84:87]
	v_mfma_f32_16x16x32_bf16 v[84:87], v[172:175], v[196:199], v[84:87]
	v_mfma_f32_16x16x32_bf16 v[68:71], v[168:171], v[200:203], v[68:71]
	v_mfma_f32_16x16x32_bf16 v[68:71], v[172:175], v[204:207], v[68:71]
	s_setprio 0
	s_barrier
	s_mov_b32 m0, s23
	v_lshl_add_u64 v[208:209], s[12:13], 0, v[2:3]
	s_add_u32 s52, s12, 0x80000
	ds_read_b128 v[176:179], v127 offset:16384
	ds_read_b128 v[180:183], v127 offset:17408
	ds_read_b128 v[184:187], v127 offset:18432
	ds_read_b128 v[188:191], v127 offset:19456
	ds_read_b128 v[192:195], v127 offset:20480
	ds_read_b128 v[196:199], v127 offset:21504
	ds_read_b128 v[200:203], v127 offset:22528
	ds_read_b128 v[204:207], v127 offset:23552
	global_load_lds_dwordx4 v[208:209], off
	v_lshl_add_u64 v[210:211], s[12:13], 0, v[120:121]
	s_mov_b32 m0, s24
	s_addc_u32 s53, s13, 0
	global_load_lds_dwordx4 v[210:211], off
	v_lshl_add_u64 v[216:217], s[52:53], 0, v[2:3]
	s_mov_b32 m0, s25
	v_lshl_add_u64 v[218:219], s[14:15], 0, v[118:119]
	global_load_lds_dwordx4 v[216:217], off
	v_lshl_add_u64 v[216:217], s[52:53], 0, v[120:121]
	s_mov_b32 m0, s26
	s_nop 0
	global_load_lds_dwordx4 v[216:217], off
	v_lshl_add_u64 v[216:217], s[14:15], 0, v[116:117]
	s_mov_b32 m0, s27
	s_nop 0
	global_load_lds_dwordx4 v[216:217], off
	s_mov_b32 m0, s35
	s_nop 0
	global_load_lds_dwordx4 v[218:219], off
	s_waitcnt vmcnt(8)
	s_waitcnt lgkmcnt(0)
	s_barrier
	s_setprio 1
	s_waitcnt lgkmcnt(0)
	v_mfma_f32_16x16x32_bf16 v[64:67], v[128:131], v[176:179], v[64:67]
	v_mfma_f32_16x16x32_bf16 v[64:67], v[132:135], v[180:183], v[64:67]
	v_mfma_f32_16x16x32_bf16 v[48:51], v[128:131], v[184:187], v[48:51]
	v_mfma_f32_16x16x32_bf16 v[48:51], v[132:135], v[188:191], v[48:51]
	v_mfma_f32_16x16x32_bf16 v[32:35], v[128:131], v[192:195], v[32:35]
	v_mfma_f32_16x16x32_bf16 v[32:35], v[132:135], v[196:199], v[32:35]
	v_mfma_f32_16x16x32_bf16 v[16:19], v[128:131], v[200:203], v[16:19]
	v_mfma_f32_16x16x32_bf16 v[16:19], v[132:135], v[204:207], v[16:19]
	v_mfma_f32_16x16x32_bf16 v[60:63], v[140:143], v[176:179], v[60:63]
	v_mfma_f32_16x16x32_bf16 v[60:63], v[148:151], v[180:183], v[60:63]
	v_mfma_f32_16x16x32_bf16 v[44:47], v[140:143], v[184:187], v[44:47]
	v_mfma_f32_16x16x32_bf16 v[44:47], v[148:151], v[188:191], v[44:47]
	v_mfma_f32_16x16x32_bf16 v[28:31], v[140:143], v[192:195], v[28:31]
	v_mfma_f32_16x16x32_bf16 v[28:31], v[148:151], v[196:199], v[28:31]
	v_mfma_f32_16x16x32_bf16 v[12:15], v[140:143], v[200:203], v[12:15]
	v_mfma_f32_16x16x32_bf16 v[12:15], v[148:151], v[204:207], v[12:15]
	s_setprio 0
	s_setprio 1
	v_mfma_f32_16x16x32_bf16 v[56:59], v[160:163], v[176:179], v[56:59]
	v_mfma_f32_16x16x32_bf16 v[56:59], v[164:167], v[180:183], v[56:59]
	v_mfma_f32_16x16x32_bf16 v[40:43], v[160:163], v[184:187], v[40:43]
	v_mfma_f32_16x16x32_bf16 v[40:43], v[164:167], v[188:191], v[40:43]
	v_mfma_f32_16x16x32_bf16 v[24:27], v[160:163], v[192:195], v[24:27]
	v_mfma_f32_16x16x32_bf16 v[24:27], v[164:167], v[196:199], v[24:27]
	v_mfma_f32_16x16x32_bf16 v[8:11], v[160:163], v[200:203], v[8:11]
	v_mfma_f32_16x16x32_bf16 v[8:11], v[164:167], v[204:207], v[8:11]
	v_mfma_f32_16x16x32_bf16 v[52:55], v[168:171], v[176:179], v[52:55]
	v_mfma_f32_16x16x32_bf16 v[52:55], v[172:175], v[180:183], v[52:55]
	v_mfma_f32_16x16x32_bf16 v[36:39], v[168:171], v[184:187], v[36:39]
	v_mfma_f32_16x16x32_bf16 v[36:39], v[172:175], v[188:191], v[36:39]
	v_mfma_f32_16x16x32_bf16 v[20:23], v[168:171], v[192:195], v[20:23]
	v_mfma_f32_16x16x32_bf16 v[20:23], v[172:175], v[196:199], v[20:23]
	v_mfma_f32_16x16x32_bf16 v[4:7], v[168:171], v[200:203], v[4:7]
	v_mfma_f32_16x16x32_bf16 v[4:7], v[172:175], v[204:207], v[4:7]
	s_setprio 0
	s_barrier
	v_add_u32_e32 v148, s20, v126
	v_add_u32_e32 v172, s21, v126
	ds_read_b128 v[128:131], v148
	ds_read_b128 v[132:135], v148 offset:1024
	ds_read_b128 v[140:143], v148 offset:2048
	ds_read_b128 v[148:151], v148 offset:3072
	ds_read_b128 v[160:163], v172
	ds_read_b128 v[164:167], v172 offset:1024
	ds_read_b128 v[168:171], v172 offset:2048
	ds_read_b128 v[172:175], v172 offset:3072
	s_add_u32 s14, s14, 0x80000
	s_addc_u32 s15, s15, 0
	s_mov_b32 m0, s37
	v_lshl_add_u64 v[220:221], s[14:15], 0, v[116:117]
	ds_read_b128 v[176:179], v127 offset:32768
	ds_read_b128 v[180:183], v127 offset:33792
	ds_read_b128 v[184:187], v127 offset:34816
	ds_read_b128 v[188:191], v127 offset:35840
	ds_read_b128 v[192:195], v127 offset:36864
	ds_read_b128 v[196:199], v127 offset:37888
	ds_read_b128 v[200:203], v127 offset:38912
	ds_read_b128 v[204:207], v127 offset:39936
	global_load_lds_dwordx4 v[220:221], off
	v_lshl_add_u64 v[220:221], s[14:15], 0, v[118:119]
	s_mov_b32 m0, s38
	s_nop 0
	global_load_lds_dwordx4 v[220:221], off
	s_waitcnt vmcnt(8)
	s_waitcnt lgkmcnt(0)
	s_barrier
	s_setprio 1
	s_waitcnt lgkmcnt(0)
	v_mfma_f32_16x16x32_bf16 v[156:159], v[128:131], v[176:179], v[156:159]
	v_mfma_f32_16x16x32_bf16 v[156:159], v[132:135], v[180:183], v[156:159]
	v_mfma_f32_16x16x32_bf16 v[112:115], v[128:131], v[184:187], v[112:115]
	v_mfma_f32_16x16x32_bf16 v[112:115], v[132:135], v[188:191], v[112:115]
	v_mfma_f32_16x16x32_bf16 v[96:99], v[128:131], v[192:195], v[96:99]
	v_mfma_f32_16x16x32_bf16 v[96:99], v[132:135], v[196:199], v[96:99]
	v_mfma_f32_16x16x32_bf16 v[80:83], v[128:131], v[200:203], v[80:83]
	v_mfma_f32_16x16x32_bf16 v[80:83], v[132:135], v[204:207], v[80:83]
	v_mfma_f32_16x16x32_bf16 v[152:155], v[140:143], v[176:179], v[152:155]
	v_mfma_f32_16x16x32_bf16 v[152:155], v[148:151], v[180:183], v[152:155]
	v_mfma_f32_16x16x32_bf16 v[108:111], v[140:143], v[184:187], v[108:111]
	v_mfma_f32_16x16x32_bf16 v[108:111], v[148:151], v[188:191], v[108:111]
	v_mfma_f32_16x16x32_bf16 v[92:95], v[140:143], v[192:195], v[92:95]
	v_mfma_f32_16x16x32_bf16 v[92:95], v[148:151], v[196:199], v[92:95]
	v_mfma_f32_16x16x32_bf16 v[76:79], v[140:143], v[200:203], v[76:79]
	v_mfma_f32_16x16x32_bf16 v[76:79], v[148:151], v[204:207], v[76:79]
	s_setprio 0
	s_setprio 1
	v_mfma_f32_16x16x32_bf16 v[144:147], v[160:163], v[176:179], v[144:147]
	v_mfma_f32_16x16x32_bf16 v[144:147], v[164:167], v[180:183], v[144:147]
	v_mfma_f32_16x16x32_bf16 v[104:107], v[160:163], v[184:187], v[104:107]
	v_mfma_f32_16x16x32_bf16 v[104:107], v[164:167], v[188:191], v[104:107]
	v_mfma_f32_16x16x32_bf16 v[88:91], v[160:163], v[192:195], v[88:91]
	v_mfma_f32_16x16x32_bf16 v[88:91], v[164:167], v[196:199], v[88:91]
	v_mfma_f32_16x16x32_bf16 v[72:75], v[160:163], v[200:203], v[72:75]
	v_mfma_f32_16x16x32_bf16 v[72:75], v[164:167], v[204:207], v[72:75]
	v_mfma_f32_16x16x32_bf16 v[136:139], v[168:171], v[176:179], v[136:139]
	v_mfma_f32_16x16x32_bf16 v[136:139], v[172:175], v[180:183], v[136:139]
	v_mfma_f32_16x16x32_bf16 v[100:103], v[168:171], v[184:187], v[100:103]
	v_mfma_f32_16x16x32_bf16 v[100:103], v[172:175], v[188:191], v[100:103]
	v_mfma_f32_16x16x32_bf16 v[84:87], v[168:171], v[192:195], v[84:87]
	v_mfma_f32_16x16x32_bf16 v[84:87], v[172:175], v[196:199], v[84:87]
	v_mfma_f32_16x16x32_bf16 v[68:71], v[168:171], v[200:203], v[68:71]
	v_mfma_f32_16x16x32_bf16 v[68:71], v[172:175], v[204:207], v[68:71]
	s_setprio 0
	s_barrier
	s_mov_b32 m0, s40
	v_lshl_add_u64 v[208:209], v[208:209], 0, s[64:65]
	s_add_u32 s12, s12, 0x80080
	ds_read_b128 v[176:179], v127 offset:49152
	ds_read_b128 v[180:183], v127 offset:50176
	ds_read_b128 v[184:187], v127 offset:51200
	ds_read_b128 v[188:191], v127 offset:52224
	ds_read_b128 v[192:195], v127 offset:53248
	ds_read_b128 v[196:199], v127 offset:54272
	ds_read_b128 v[200:203], v127 offset:55296
	ds_read_b128 v[204:207], v127 offset:56320
	global_load_lds_dwordx4 v[208:209], off
	v_lshl_add_u64 v[208:209], v[210:211], 0, s[64:65]
	s_mov_b32 m0, s41
	s_addc_u32 s13, s13, 0
	global_load_lds_dwordx4 v[208:209], off
	v_lshl_add_u64 v[208:209], s[12:13], 0, v[2:3]
	s_mov_b32 m0, s44
	s_nop 0
	global_load_lds_dwordx4 v[208:209], off
	v_lshl_add_u64 v[208:209], s[12:13], 0, v[120:121]
	s_mov_b32 m0, s45
	s_nop 0
	global_load_lds_dwordx4 v[208:209], off
	v_lshl_add_u64 v[208:209], v[216:217], 0, s[64:65]
	s_mov_b32 m0, s42
	s_nop 0
	global_load_lds_dwordx4 v[208:209], off
	v_lshl_add_u64 v[208:209], v[218:219], 0, s[64:65]
	s_mov_b32 m0, s43
	s_nop 0
	global_load_lds_dwordx4 v[208:209], off
	s_waitcnt vmcnt(8)
	s_waitcnt lgkmcnt(0)
	s_barrier
	s_setprio 1
	s_waitcnt lgkmcnt(0)
	v_mfma_f32_16x16x32_bf16 v[64:67], v[128:131], v[176:179], v[64:67]
	v_mfma_f32_16x16x32_bf16 v[64:67], v[132:135], v[180:183], v[64:67]
	v_mfma_f32_16x16x32_bf16 v[48:51], v[128:131], v[184:187], v[48:51]
	v_mfma_f32_16x16x32_bf16 v[48:51], v[132:135], v[188:191], v[48:51]
	v_mfma_f32_16x16x32_bf16 v[32:35], v[128:131], v[192:195], v[32:35]
	v_mfma_f32_16x16x32_bf16 v[32:35], v[132:135], v[196:199], v[32:35]
	v_mfma_f32_16x16x32_bf16 v[16:19], v[128:131], v[200:203], v[16:19]
	v_mfma_f32_16x16x32_bf16 v[16:19], v[132:135], v[204:207], v[16:19]
	v_mfma_f32_16x16x32_bf16 v[60:63], v[140:143], v[176:179], v[60:63]
	v_mfma_f32_16x16x32_bf16 v[60:63], v[148:151], v[180:183], v[60:63]
	v_mfma_f32_16x16x32_bf16 v[44:47], v[140:143], v[184:187], v[44:47]
	v_mfma_f32_16x16x32_bf16 v[44:47], v[148:151], v[188:191], v[44:47]
	v_mfma_f32_16x16x32_bf16 v[28:31], v[140:143], v[192:195], v[28:31]
	v_mfma_f32_16x16x32_bf16 v[28:31], v[148:151], v[196:199], v[28:31]
	v_mfma_f32_16x16x32_bf16 v[12:15], v[140:143], v[200:203], v[12:15]
	v_mfma_f32_16x16x32_bf16 v[12:15], v[148:151], v[204:207], v[12:15]
	s_setprio 0
	s_setprio 1
	v_mfma_f32_16x16x32_bf16 v[56:59], v[160:163], v[176:179], v[56:59]
	v_mfma_f32_16x16x32_bf16 v[56:59], v[164:167], v[180:183], v[56:59]
	v_mfma_f32_16x16x32_bf16 v[40:43], v[160:163], v[184:187], v[40:43]
	v_mfma_f32_16x16x32_bf16 v[40:43], v[164:167], v[188:191], v[40:43]
	v_mfma_f32_16x16x32_bf16 v[24:27], v[160:163], v[192:195], v[24:27]
	v_mfma_f32_16x16x32_bf16 v[24:27], v[164:167], v[196:199], v[24:27]
	v_mfma_f32_16x16x32_bf16 v[8:11], v[160:163], v[200:203], v[8:11]
	v_mfma_f32_16x16x32_bf16 v[8:11], v[164:167], v[204:207], v[8:11]
	v_mfma_f32_16x16x32_bf16 v[52:55], v[168:171], v[176:179], v[52:55]
	v_mfma_f32_16x16x32_bf16 v[52:55], v[172:175], v[180:183], v[52:55]
	v_mfma_f32_16x16x32_bf16 v[36:39], v[168:171], v[184:187], v[36:39]
	v_mfma_f32_16x16x32_bf16 v[36:39], v[172:175], v[188:191], v[36:39]
	v_mfma_f32_16x16x32_bf16 v[20:23], v[168:171], v[192:195], v[20:23]
	v_mfma_f32_16x16x32_bf16 v[20:23], v[172:175], v[196:199], v[20:23]
	v_mfma_f32_16x16x32_bf16 v[4:7], v[168:171], v[200:203], v[4:7]
	v_mfma_f32_16x16x32_bf16 v[4:7], v[172:175], v[204:207], v[4:7]
	s_setprio 0
	s_barrier
	s_add_i32 s50, s50, 2
	s_add_u32 s8, s8, 0x100
	s_addc_u32 s9, s9, 0
	s_cmp_gt_u32 s50, 29
	s_cbranch_scc0 .LBB0_2896
	s_cmpk_lt_u32 s22, 0x100
	s_cbranch_scc0 .LBB0_2899
	s_barrier

.LBB0_3116:
	v_add_u32_e32 v142, s26, v144
	ds_read_b128 v[146:149], v142
	ds_read_b128 v[150:153], v142 offset:1024
	ds_read_b128 v[154:157], v142 offset:2048
	ds_read_b128 v[158:161], v142 offset:3072
	v_add_u32_e32 v142, s40, v144
	ds_read_b128 v[162:165], v142
	ds_read_b128 v[166:169], v142 offset:1024
	ds_read_b128 v[170:173], v142 offset:2048
	ds_read_b128 v[174:177], v142 offset:3072
	s_add_u32 s18, s34, 0xfff80080
	s_addc_u32 s19, s35, -1
	s_cmp_eq_u32 s74, 28
	s_cselect_b32 s39, s13, s19
	s_cselect_b32 s38, s69, s18
	s_cselect_b32 s19, s11, s73
	s_cselect_b32 s18, s70, s71
	v_lshl_add_u64 v[142:143], s[34:35], 0, v[138:139]
	s_add_i32 m0, s43, 0xc000
	ds_read_b128 v[178:181], v145
	ds_read_b128 v[182:185], v145 offset:1024
	ds_read_b128 v[186:189], v145 offset:2048
	ds_read_b128 v[190:193], v145 offset:3072
	ds_read_b128 v[194:197], v145 offset:4096
	ds_read_b128 v[198:201], v145 offset:5120
	ds_read_b128 v[202:205], v145 offset:6144
	ds_read_b128 v[206:209], v145 offset:7168
	global_load_lds_dwordx4 v[142:143], off
	v_lshl_add_u64 v[142:143], s[34:35], 0, v[140:141]
	s_add_i32 m0, s43, 0xe000
	s_nop 0
	global_load_lds_dwordx4 v[142:143], off
	s_waitcnt vmcnt(8)
	s_waitcnt lgkmcnt(0)
	s_barrier
	s_setprio 1
	s_waitcnt lgkmcnt(0)
	v_mfma_f32_16x16x32_bf16 v[128:131], v[146:149], v[178:181], v[128:131]
	v_mfma_f32_16x16x32_bf16 v[128:131], v[150:153], v[182:185], v[128:131]
	v_mfma_f32_16x16x32_bf16 v[112:115], v[146:149], v[186:189], v[112:115]
	v_mfma_f32_16x16x32_bf16 v[112:115], v[150:153], v[190:193], v[112:115]
	v_mfma_f32_16x16x32_bf16 v[96:99], v[146:149], v[194:197], v[96:99]
	v_mfma_f32_16x16x32_bf16 v[96:99], v[150:153], v[198:201], v[96:99]
	v_mfma_f32_16x16x32_bf16 v[80:83], v[146:149], v[202:205], v[80:83]
	v_mfma_f32_16x16x32_bf16 v[80:83], v[150:153], v[206:209], v[80:83]
	v_mfma_f32_16x16x32_bf16 v[120:123], v[154:157], v[178:181], v[120:123]
	v_mfma_f32_16x16x32_bf16 v[120:123], v[158:161], v[182:185], v[120:123]
	v_mfma_f32_16x16x32_bf16 v[104:107], v[154:157], v[186:189], v[104:107]
	v_mfma_f32_16x16x32_bf16 v[104:107], v[158:161], v[190:193], v[104:107]
	v_mfma_f32_16x16x32_bf16 v[88:91], v[154:157], v[194:197], v[88:91]
	v_mfma_f32_16x16x32_bf16 v[88:91], v[158:161], v[198:201], v[88:91]
	v_mfma_f32_16x16x32_bf16 v[72:75], v[154:157], v[202:205], v[72:75]
	v_mfma_f32_16x16x32_bf16 v[72:75], v[158:161], v[206:209], v[72:75]
	s_setprio 0
	s_setprio 1
	v_mfma_f32_16x16x32_bf16 v[124:127], v[162:165], v[178:181], v[124:127]
	v_mfma_f32_16x16x32_bf16 v[124:127], v[166:169], v[182:185], v[124:127]
	v_mfma_f32_16x16x32_bf16 v[108:111], v[162:165], v[186:189], v[108:111]
	v_mfma_f32_16x16x32_bf16 v[108:111], v[166:169], v[190:193], v[108:111]
	v_mfma_f32_16x16x32_bf16 v[92:95], v[162:165], v[194:197], v[92:95]
	v_mfma_f32_16x16x32_bf16 v[92:95], v[166:169], v[198:201], v[92:95]
	v_mfma_f32_16x16x32_bf16 v[76:79], v[162:165], v[202:205], v[76:79]
	v_mfma_f32_16x16x32_bf16 v[76:79], v[166:169], v[206:209], v[76:79]
	v_mfma_f32_16x16x32_bf16 v[116:119], v[170:173], v[178:181], v[116:119]
	v_mfma_f32_16x16x32_bf16 v[116:119], v[174:177], v[182:185], v[116:119]
	v_mfma_f32_16x16x32_bf16 v[100:103], v[170:173], v[186:189], v[100:103]
	v_mfma_f32_16x16x32_bf16 v[100:103], v[174:177], v[190:193], v[100:103]
	v_mfma_f32_16x16x32_bf16 v[84:87], v[170:173], v[194:197], v[84:87]
	v_mfma_f32_16x16x32_bf16 v[84:87], v[174:177], v[198:201], v[84:87]
	v_mfma_f32_16x16x32_bf16 v[68:71], v[170:173], v[202:205], v[68:71]
	v_mfma_f32_16x16x32_bf16 v[68:71], v[174:177], v[206:209], v[68:71]
	s_setprio 0
	s_barrier
	s_mov_b32 m0, s27
	v_lshl_add_u64 v[142:143], s[18:19], 0, v[2:3]
	s_add_u32 s76, s18, 0x80000
	ds_read_b128 v[178:181], v145 offset:16384
	ds_read_b128 v[182:185], v145 offset:17408
	ds_read_b128 v[186:189], v145 offset:18432
	ds_read_b128 v[190:193], v145 offset:19456
	ds_read_b128 v[194:197], v145 offset:20480
	ds_read_b128 v[198:201], v145 offset:21504
	ds_read_b128 v[202:205], v145 offset:22528
	ds_read_b128 v[206:209], v145 offset:23552
	global_load_lds_dwordx4 v[142:143], off
	v_lshl_add_u64 v[210:211], s[18:19], 0, v[132:133]
	s_mov_b32 m0, s37
	s_addc_u32 s77, s19, 0
	global_load_lds_dwordx4 v[210:211], off
	v_lshl_add_u64 v[212:213], s[76:77], 0, v[2:3]
	s_mov_b32 m0, s41
	v_lshl_add_u64 v[214:215], s[38:39], 0, v[134:135]
	global_load_lds_dwordx4 v[212:213], off
	v_lshl_add_u64 v[212:213], s[76:77], 0, v[132:133]
	s_mov_b32 m0, s42
	s_nop 0
	global_load_lds_dwordx4 v[212:213], off
	v_lshl_add_u64 v[212:213], s[38:39], 0, v[136:137]
	s_mov_b32 m0, s43
	s_nop 0
	global_load_lds_dwordx4 v[212:213], off
	s_mov_b32 m0, s44
	s_nop 0
	global_load_lds_dwordx4 v[214:215], off
	s_waitcnt vmcnt(8)
	s_waitcnt lgkmcnt(0)
	s_barrier
	s_setprio 1
	s_waitcnt lgkmcnt(0)
	v_mfma_f32_16x16x32_bf16 v[64:67], v[146:149], v[178:181], v[64:67]
	v_mfma_f32_16x16x32_bf16 v[64:67], v[150:153], v[182:185], v[64:67]
	v_mfma_f32_16x16x32_bf16 v[48:51], v[146:149], v[186:189], v[48:51]
	v_mfma_f32_16x16x32_bf16 v[48:51], v[150:153], v[190:193], v[48:51]
	v_mfma_f32_16x16x32_bf16 v[32:35], v[146:149], v[194:197], v[32:35]
	v_mfma_f32_16x16x32_bf16 v[32:35], v[150:153], v[198:201], v[32:35]
	v_mfma_f32_16x16x32_bf16 v[16:19], v[146:149], v[202:205], v[16:19]
	v_mfma_f32_16x16x32_bf16 v[16:19], v[150:153], v[206:209], v[16:19]
	v_mfma_f32_16x16x32_bf16 v[56:59], v[154:157], v[178:181], v[56:59]
	v_mfma_f32_16x16x32_bf16 v[56:59], v[158:161], v[182:185], v[56:59]
	v_mfma_f32_16x16x32_bf16 v[40:43], v[154:157], v[186:189], v[40:43]
	v_mfma_f32_16x16x32_bf16 v[40:43], v[158:161], v[190:193], v[40:43]
	v_mfma_f32_16x16x32_bf16 v[24:27], v[154:157], v[194:197], v[24:27]
	v_mfma_f32_16x16x32_bf16 v[24:27], v[158:161], v[198:201], v[24:27]
	v_mfma_f32_16x16x32_bf16 v[8:11], v[154:157], v[202:205], v[8:11]
	v_mfma_f32_16x16x32_bf16 v[8:11], v[158:161], v[206:209], v[8:11]
	s_setprio 0
	s_setprio 1
	v_mfma_f32_16x16x32_bf16 v[60:63], v[162:165], v[178:181], v[60:63]
	v_mfma_f32_16x16x32_bf16 v[60:63], v[166:169], v[182:185], v[60:63]
	v_mfma_f32_16x16x32_bf16 v[44:47], v[162:165], v[186:189], v[44:47]
	v_mfma_f32_16x16x32_bf16 v[44:47], v[166:169], v[190:193], v[44:47]
	v_mfma_f32_16x16x32_bf16 v[28:31], v[162:165], v[194:197], v[28:31]
	v_mfma_f32_16x16x32_bf16 v[28:31], v[166:169], v[198:201], v[28:31]
	v_mfma_f32_16x16x32_bf16 v[12:15], v[162:165], v[202:205], v[12:15]
	v_mfma_f32_16x16x32_bf16 v[12:15], v[166:169], v[206:209], v[12:15]
	v_mfma_f32_16x16x32_bf16 v[52:55], v[170:173], v[178:181], v[52:55]
	v_mfma_f32_16x16x32_bf16 v[52:55], v[174:177], v[182:185], v[52:55]
	v_mfma_f32_16x16x32_bf16 v[36:39], v[170:173], v[186:189], v[36:39]
	v_mfma_f32_16x16x32_bf16 v[36:39], v[174:177], v[190:193], v[36:39]
	v_mfma_f32_16x16x32_bf16 v[20:23], v[170:173], v[194:197], v[20:23]
	v_mfma_f32_16x16x32_bf16 v[20:23], v[174:177], v[198:201], v[20:23]
	v_mfma_f32_16x16x32_bf16 v[4:7], v[170:173], v[202:205], v[4:7]
	v_mfma_f32_16x16x32_bf16 v[4:7], v[174:177], v[206:209], v[4:7]
	s_setprio 0
	s_barrier
	v_add_u32_e32 v158, s49, v144
	v_add_u32_e32 v174, s56, v144
	ds_read_b128 v[146:149], v158
	ds_read_b128 v[150:153], v158 offset:1024
	ds_read_b128 v[154:157], v158 offset:2048
	ds_read_b128 v[158:161], v158 offset:3072
	ds_read_b128 v[162:165], v174
	ds_read_b128 v[166:169], v174 offset:1024
	ds_read_b128 v[170:173], v174 offset:2048
	ds_read_b128 v[174:177], v174 offset:3072
	s_add_u32 s38, s38, 0x80000
	s_addc_u32 s39, s39, 0
	s_mov_b32 m0, s45
	v_lshl_add_u64 v[216:217], s[38:39], 0, v[136:137]
	ds_read_b128 v[178:181], v145 offset:32768
	ds_read_b128 v[182:185], v145 offset:33792
	ds_read_b128 v[186:189], v145 offset:34816
	ds_read_b128 v[190:193], v145 offset:35840
	ds_read_b128 v[194:197], v145 offset:36864
	ds_read_b128 v[198:201], v145 offset:37888
	ds_read_b128 v[202:205], v145 offset:38912
	ds_read_b128 v[206:209], v145 offset:39936
	global_load_lds_dwordx4 v[216:217], off
	v_lshl_add_u64 v[216:217], s[38:39], 0, v[134:135]
	s_mov_b32 m0, s46
	s_nop 0
	global_load_lds_dwordx4 v[216:217], off
	s_waitcnt vmcnt(8)
	s_waitcnt lgkmcnt(0)
	s_barrier
	s_setprio 1
	s_waitcnt lgkmcnt(0)
	v_mfma_f32_16x16x32_bf16 v[128:131], v[146:149], v[178:181], v[128:131]
	v_mfma_f32_16x16x32_bf16 v[128:131], v[150:153], v[182:185], v[128:131]
	v_mfma_f32_16x16x32_bf16 v[112:115], v[146:149], v[186:189], v[112:115]
	v_mfma_f32_16x16x32_bf16 v[112:115], v[150:153], v[190:193], v[112:115]
	v_mfma_f32_16x16x32_bf16 v[96:99], v[146:149], v[194:197], v[96:99]
	v_mfma_f32_16x16x32_bf16 v[96:99], v[150:153], v[198:201], v[96:99]
	v_mfma_f32_16x16x32_bf16 v[80:83], v[146:149], v[202:205], v[80:83]
	v_mfma_f32_16x16x32_bf16 v[80:83], v[150:153], v[206:209], v[80:83]
	v_mfma_f32_16x16x32_bf16 v[120:123], v[154:157], v[178:181], v[120:123]
	v_mfma_f32_16x16x32_bf16 v[120:123], v[158:161], v[182:185], v[120:123]
	v_mfma_f32_16x16x32_bf16 v[104:107], v[154:157], v[186:189], v[104:107]
	v_mfma_f32_16x16x32_bf16 v[104:107], v[158:161], v[190:193], v[104:107]
	v_mfma_f32_16x16x32_bf16 v[88:91], v[154:157], v[194:197], v[88:91]
	v_mfma_f32_16x16x32_bf16 v[88:91], v[158:161], v[198:201], v[88:91]
	v_mfma_f32_16x16x32_bf16 v[72:75], v[154:157], v[202:205], v[72:75]
	v_mfma_f32_16x16x32_bf16 v[72:75], v[158:161], v[206:209], v[72:75]
	s_setprio 0
	s_setprio 1
	v_mfma_f32_16x16x32_bf16 v[124:127], v[162:165], v[178:181], v[124:127]
	v_mfma_f32_16x16x32_bf16 v[124:127], v[166:169], v[182:185], v[124:127]
	v_mfma_f32_16x16x32_bf16 v[108:111], v[162:165], v[186:189], v[108:111]
	v_mfma_f32_16x16x32_bf16 v[108:111], v[166:169], v[190:193], v[108:111]
	v_mfma_f32_16x16x32_bf16 v[92:95], v[162:165], v[194:197], v[92:95]
	v_mfma_f32_16x16x32_bf16 v[92:95], v[166:169], v[198:201], v[92:95]
	v_mfma_f32_16x16x32_bf16 v[76:79], v[162:165], v[202:205], v[76:79]
	v_mfma_f32_16x16x32_bf16 v[76:79], v[166:169], v[206:209], v[76:79]
	v_mfma_f32_16x16x32_bf16 v[116:119], v[170:173], v[178:181], v[116:119]
	v_mfma_f32_16x16x32_bf16 v[116:119], v[174:177], v[182:185], v[116:119]
	v_mfma_f32_16x16x32_bf16 v[100:103], v[170:173], v[186:189], v[100:103]
	v_mfma_f32_16x16x32_bf16 v[100:103], v[174:177], v[190:193], v[100:103]
	v_mfma_f32_16x16x32_bf16 v[84:87], v[170:173], v[194:197], v[84:87]
	v_mfma_f32_16x16x32_bf16 v[84:87], v[174:177], v[198:201], v[84:87]
	v_mfma_f32_16x16x32_bf16 v[68:71], v[170:173], v[202:205], v[68:71]
	v_mfma_f32_16x16x32_bf16 v[68:71], v[174:177], v[206:209], v[68:71]
	s_setprio 0
	s_barrier
	s_mov_b32 m0, s50
	v_lshl_add_u64 v[142:143], v[142:143], 0, s[64:65]
	s_add_u32 s18, s18, 0x80080
	ds_read_b128 v[178:181], v145 offset:49152
	ds_read_b128 v[182:185], v145 offset:50176
	ds_read_b128 v[186:189], v145 offset:51200
	ds_read_b128 v[190:193], v145 offset:52224
	ds_read_b128 v[194:197], v145 offset:53248
	ds_read_b128 v[198:201], v145 offset:54272
	ds_read_b128 v[202:205], v145 offset:55296
	ds_read_b128 v[206:209], v145 offset:56320
	global_load_lds_dwordx4 v[142:143], off
	v_lshl_add_u64 v[142:143], v[210:211], 0, s[64:65]
	s_mov_b32 m0, s51
	s_addc_u32 s19, s19, 0
	global_load_lds_dwordx4 v[142:143], off
	v_lshl_add_u64 v[142:143], s[18:19], 0, v[2:3]
	s_mov_b32 m0, s57
	s_nop 0
	global_load_lds_dwordx4 v[142:143], off
	v_lshl_add_u64 v[142:143], s[18:19], 0, v[132:133]
	s_mov_b32 m0, s58
	s_nop 0
	global_load_lds_dwordx4 v[142:143], off
	v_lshl_add_u64 v[142:143], v[212:213], 0, s[64:65]
	s_mov_b32 m0, s52
	s_nop 0
	global_load_lds_dwordx4 v[142:143], off
	v_lshl_add_u64 v[142:143], v[214:215], 0, s[64:65]
	s_mov_b32 m0, s53
	s_nop 0
	global_load_lds_dwordx4 v[142:143], off
	s_waitcnt vmcnt(8)
	s_waitcnt lgkmcnt(0)
	s_barrier
	s_setprio 1
	s_waitcnt lgkmcnt(0)
	v_mfma_f32_16x16x32_bf16 v[64:67], v[146:149], v[178:181], v[64:67]
	v_mfma_f32_16x16x32_bf16 v[64:67], v[150:153], v[182:185], v[64:67]
	v_mfma_f32_16x16x32_bf16 v[48:51], v[146:149], v[186:189], v[48:51]
	v_mfma_f32_16x16x32_bf16 v[48:51], v[150:153], v[190:193], v[48:51]
	v_mfma_f32_16x16x32_bf16 v[32:35], v[146:149], v[194:197], v[32:35]
	v_mfma_f32_16x16x32_bf16 v[32:35], v[150:153], v[198:201], v[32:35]
	v_mfma_f32_16x16x32_bf16 v[16:19], v[146:149], v[202:205], v[16:19]
	v_mfma_f32_16x16x32_bf16 v[16:19], v[150:153], v[206:209], v[16:19]
	v_mfma_f32_16x16x32_bf16 v[56:59], v[154:157], v[178:181], v[56:59]
	v_mfma_f32_16x16x32_bf16 v[56:59], v[158:161], v[182:185], v[56:59]
	v_mfma_f32_16x16x32_bf16 v[40:43], v[154:157], v[186:189], v[40:43]
	v_mfma_f32_16x16x32_bf16 v[40:43], v[158:161], v[190:193], v[40:43]
	v_mfma_f32_16x16x32_bf16 v[24:27], v[154:157], v[194:197], v[24:27]
	v_mfma_f32_16x16x32_bf16 v[24:27], v[158:161], v[198:201], v[24:27]
	v_mfma_f32_16x16x32_bf16 v[8:11], v[154:157], v[202:205], v[8:11]
	v_mfma_f32_16x16x32_bf16 v[8:11], v[158:161], v[206:209], v[8:11]
	s_setprio 0
	s_setprio 1
	v_mfma_f32_16x16x32_bf16 v[60:63], v[162:165], v[178:181], v[60:63]
	v_mfma_f32_16x16x32_bf16 v[60:63], v[166:169], v[182:185], v[60:63]
	v_mfma_f32_16x16x32_bf16 v[44:47], v[162:165], v[186:189], v[44:47]
	v_mfma_f32_16x16x32_bf16 v[44:47], v[166:169], v[190:193], v[44:47]
	v_mfma_f32_16x16x32_bf16 v[28:31], v[162:165], v[194:197], v[28:31]
	v_mfma_f32_16x16x32_bf16 v[28:31], v[166:169], v[198:201], v[28:31]
	v_mfma_f32_16x16x32_bf16 v[12:15], v[162:165], v[202:205], v[12:15]
	v_mfma_f32_16x16x32_bf16 v[12:15], v[166:169], v[206:209], v[12:15]
	v_mfma_f32_16x16x32_bf16 v[52:55], v[170:173], v[178:181], v[52:55]
	v_mfma_f32_16x16x32_bf16 v[52:55], v[174:177], v[182:185], v[52:55]
	v_mfma_f32_16x16x32_bf16 v[36:39], v[170:173], v[186:189], v[36:39]
	v_mfma_f32_16x16x32_bf16 v[36:39], v[174:177], v[190:193], v[36:39]
	v_mfma_f32_16x16x32_bf16 v[20:23], v[170:173], v[194:197], v[20:23]
	v_mfma_f32_16x16x32_bf16 v[20:23], v[174:177], v[198:201], v[20:23]
	v_mfma_f32_16x16x32_bf16 v[4:7], v[170:173], v[202:205], v[4:7]
	v_mfma_f32_16x16x32_bf16 v[4:7], v[174:177], v[206:209], v[4:7]
	s_setprio 0
	s_barrier
	s_add_i32 s74, s74, 2
	s_add_u32 s34, s34, 0x100
	s_addc_u32 s35, s35, 0
	s_add_u32 s71, s71, 0x100
	s_addc_u32 s73, s73, 0
	s_cmp_gt_u32 s74, 29
	s_cbranch_scc0 .LBB0_3116
	s_and_b64 vcc, exec, s[8:9]
	s_cbranch_vccz .LBB0_3119
	s_barrier

.LBB0_3195:
	v_add_u32_e32 v144, s26, v249
	v_add_u32_e32 v160, s38, v249
	ds_read_b128 v[132:135], v144
	ds_read_b128 v[136:139], v144 offset:1024
	ds_read_b128 v[140:143], v144 offset:2048
	ds_read_b128 v[144:147], v144 offset:3072
	ds_read_b128 v[148:151], v160
	ds_read_b128 v[152:155], v160 offset:1024
	ds_read_b128 v[156:159], v160 offset:2048
	ds_read_b128 v[160:163], v160 offset:3072
	s_add_u32 s24, s14, 0x100
	s_addc_u32 s25, s15, 0
	s_cmpk_eq_i32 s74, 0x54
	s_cselect_b32 s35, s5, s25
	s_cselect_b32 s34, s4, s24
	s_cselect_b32 s19, s13, s73
	s_cselect_b32 s18, s12, s71
	v_lshl_add_u64 v[196:197], s[14:15], 0, v[222:223]
	s_add_i32 m0, s41, 0xc000
	ds_read_b128 v[164:167], v250
	ds_read_b128 v[168:171], v250 offset:1024
	ds_read_b128 v[172:175], v250 offset:2048
	ds_read_b128 v[176:179], v250 offset:3072
	ds_read_b128 v[180:183], v250 offset:4096
	ds_read_b128 v[184:187], v250 offset:5120
	ds_read_b128 v[188:191], v250 offset:6144
	ds_read_b128 v[192:195], v250 offset:7168
	global_load_lds_dwordx4 v[196:197], off
	v_lshl_add_u64 v[196:197], s[14:15], 0, v[224:225]
	s_add_i32 m0, s41, 0xe000
	s_nop 0
	global_load_lds_dwordx4 v[196:197], off
	s_waitcnt vmcnt(8)
	s_waitcnt lgkmcnt(0)
	s_barrier
	s_setprio 1
	s_waitcnt lgkmcnt(0)
	v_mfma_f32_16x16x32_bf16 v[128:131], v[132:135], v[164:167], v[128:131]
	v_mfma_f32_16x16x32_bf16 v[128:131], v[136:139], v[168:171], v[128:131]
	v_mfma_f32_16x16x32_bf16 v[112:115], v[132:135], v[172:175], v[112:115]
	v_mfma_f32_16x16x32_bf16 v[112:115], v[136:139], v[176:179], v[112:115]
	v_mfma_f32_16x16x32_bf16 v[96:99], v[132:135], v[180:183], v[96:99]
	v_mfma_f32_16x16x32_bf16 v[96:99], v[136:139], v[184:187], v[96:99]
	v_mfma_f32_16x16x32_bf16 v[80:83], v[132:135], v[188:191], v[80:83]
	v_mfma_f32_16x16x32_bf16 v[80:83], v[136:139], v[192:195], v[80:83]
	v_mfma_f32_16x16x32_bf16 v[124:127], v[140:143], v[164:167], v[124:127]
	v_mfma_f32_16x16x32_bf16 v[124:127], v[144:147], v[168:171], v[124:127]
	v_mfma_f32_16x16x32_bf16 v[108:111], v[140:143], v[172:175], v[108:111]
	v_mfma_f32_16x16x32_bf16 v[108:111], v[144:147], v[176:179], v[108:111]
	v_mfma_f32_16x16x32_bf16 v[92:95], v[140:143], v[180:183], v[92:95]
	v_mfma_f32_16x16x32_bf16 v[92:95], v[144:147], v[184:187], v[92:95]
	v_mfma_f32_16x16x32_bf16 v[76:79], v[140:143], v[188:191], v[76:79]
	v_mfma_f32_16x16x32_bf16 v[76:79], v[144:147], v[192:195], v[76:79]
	s_setprio 0
	s_setprio 1
	v_mfma_f32_16x16x32_bf16 v[120:123], v[148:151], v[164:167], v[120:123]
	v_mfma_f32_16x16x32_bf16 v[120:123], v[152:155], v[168:171], v[120:123]
	v_mfma_f32_16x16x32_bf16 v[104:107], v[148:151], v[172:175], v[104:107]
	v_mfma_f32_16x16x32_bf16 v[104:107], v[152:155], v[176:179], v[104:107]
	v_mfma_f32_16x16x32_bf16 v[88:91], v[148:151], v[180:183], v[88:91]
	v_mfma_f32_16x16x32_bf16 v[88:91], v[152:155], v[184:187], v[88:91]
	v_mfma_f32_16x16x32_bf16 v[72:75], v[148:151], v[188:191], v[72:75]
	v_mfma_f32_16x16x32_bf16 v[72:75], v[152:155], v[192:195], v[72:75]
	v_mfma_f32_16x16x32_bf16 v[116:119], v[156:159], v[164:167], v[116:119]
	v_mfma_f32_16x16x32_bf16 v[116:119], v[160:163], v[168:171], v[116:119]
	v_mfma_f32_16x16x32_bf16 v[100:103], v[156:159], v[172:175], v[100:103]
	v_mfma_f32_16x16x32_bf16 v[100:103], v[160:163], v[176:179], v[100:103]
	v_mfma_f32_16x16x32_bf16 v[84:87], v[156:159], v[180:183], v[84:87]
	v_mfma_f32_16x16x32_bf16 v[84:87], v[160:163], v[184:187], v[84:87]
	v_mfma_f32_16x16x32_bf16 v[68:71], v[156:159], v[188:191], v[68:71]
	v_mfma_f32_16x16x32_bf16 v[68:71], v[160:163], v[192:195], v[68:71]
	s_setprio 0
	s_barrier
	s_mov_b32 m0, s27
	v_lshl_add_u64 v[196:197], s[18:19], 0, v[2:3]
	s_add_u32 s14, s18, 0x160000
	ds_read_b128 v[164:167], v250 offset:16384
	ds_read_b128 v[168:171], v250 offset:17408
	ds_read_b128 v[172:175], v250 offset:18432
	ds_read_b128 v[176:179], v250 offset:19456
	ds_read_b128 v[180:183], v250 offset:20480
	ds_read_b128 v[184:187], v250 offset:21504
	ds_read_b128 v[188:191], v250 offset:22528
	ds_read_b128 v[192:195], v250 offset:23552
	global_load_lds_dwordx4 v[196:197], off
	v_lshl_add_u64 v[198:199], s[18:19], 0, v[216:217]
	s_mov_b32 m0, s37
	s_addc_u32 s15, s19, 0
	global_load_lds_dwordx4 v[198:199], off
	v_lshl_add_u64 v[200:201], s[14:15], 0, v[2:3]
	s_mov_b32 m0, s39
	v_lshl_add_u64 v[202:203], s[34:35], 0, v[218:219]
	global_load_lds_dwordx4 v[200:201], off
	v_lshl_add_u64 v[200:201], s[14:15], 0, v[216:217]
	s_mov_b32 m0, s40
	s_nop 0
	global_load_lds_dwordx4 v[200:201], off
	v_lshl_add_u64 v[200:201], s[34:35], 0, v[220:221]
	s_mov_b32 m0, s41
	s_nop 0
	global_load_lds_dwordx4 v[200:201], off
	s_mov_b32 m0, s42
	s_nop 0
	global_load_lds_dwordx4 v[202:203], off
	s_waitcnt vmcnt(8)
	s_waitcnt lgkmcnt(0)
	s_barrier
	s_setprio 1
	s_waitcnt lgkmcnt(0)
	v_mfma_f32_16x16x32_bf16 v[64:67], v[132:135], v[164:167], v[64:67]
	v_mfma_f32_16x16x32_bf16 v[64:67], v[136:139], v[168:171], v[64:67]
	v_mfma_f32_16x16x32_bf16 v[48:51], v[132:135], v[172:175], v[48:51]
	v_mfma_f32_16x16x32_bf16 v[48:51], v[136:139], v[176:179], v[48:51]
	v_mfma_f32_16x16x32_bf16 v[32:35], v[132:135], v[180:183], v[32:35]
	v_mfma_f32_16x16x32_bf16 v[32:35], v[136:139], v[184:187], v[32:35]
	v_mfma_f32_16x16x32_bf16 v[16:19], v[132:135], v[188:191], v[16:19]
	v_mfma_f32_16x16x32_bf16 v[16:19], v[136:139], v[192:195], v[16:19]
	v_mfma_f32_16x16x32_bf16 v[60:63], v[140:143], v[164:167], v[60:63]
	v_mfma_f32_16x16x32_bf16 v[60:63], v[144:147], v[168:171], v[60:63]
	v_mfma_f32_16x16x32_bf16 v[44:47], v[140:143], v[172:175], v[44:47]
	v_mfma_f32_16x16x32_bf16 v[44:47], v[144:147], v[176:179], v[44:47]
	v_mfma_f32_16x16x32_bf16 v[28:31], v[140:143], v[180:183], v[28:31]
	v_mfma_f32_16x16x32_bf16 v[28:31], v[144:147], v[184:187], v[28:31]
	v_mfma_f32_16x16x32_bf16 v[12:15], v[140:143], v[188:191], v[12:15]
	v_mfma_f32_16x16x32_bf16 v[12:15], v[144:147], v[192:195], v[12:15]
	s_setprio 0
	s_setprio 1
	v_mfma_f32_16x16x32_bf16 v[56:59], v[148:151], v[164:167], v[56:59]
	v_mfma_f32_16x16x32_bf16 v[56:59], v[152:155], v[168:171], v[56:59]
	v_mfma_f32_16x16x32_bf16 v[40:43], v[148:151], v[172:175], v[40:43]
	v_mfma_f32_16x16x32_bf16 v[40:43], v[152:155], v[176:179], v[40:43]
	v_mfma_f32_16x16x32_bf16 v[24:27], v[148:151], v[180:183], v[24:27]
	v_mfma_f32_16x16x32_bf16 v[24:27], v[152:155], v[184:187], v[24:27]
	v_mfma_f32_16x16x32_bf16 v[8:11], v[148:151], v[188:191], v[8:11]
	v_mfma_f32_16x16x32_bf16 v[8:11], v[152:155], v[192:195], v[8:11]
	v_mfma_f32_16x16x32_bf16 v[52:55], v[156:159], v[164:167], v[52:55]
	v_mfma_f32_16x16x32_bf16 v[52:55], v[160:163], v[168:171], v[52:55]
	v_mfma_f32_16x16x32_bf16 v[36:39], v[156:159], v[172:175], v[36:39]
	v_mfma_f32_16x16x32_bf16 v[36:39], v[160:163], v[176:179], v[36:39]
	v_mfma_f32_16x16x32_bf16 v[20:23], v[156:159], v[180:183], v[20:23]
	v_mfma_f32_16x16x32_bf16 v[20:23], v[160:163], v[184:187], v[20:23]
	v_mfma_f32_16x16x32_bf16 v[4:7], v[156:159], v[188:191], v[4:7]
	v_mfma_f32_16x16x32_bf16 v[4:7], v[160:163], v[192:195], v[4:7]
	s_setprio 0
	s_barrier
	v_add_u32_e32 v144, s49, v249
	v_add_u32_e32 v160, s56, v249
	ds_read_b128 v[132:135], v144
	ds_read_b128 v[136:139], v144 offset:1024
	ds_read_b128 v[140:143], v144 offset:2048
	ds_read_b128 v[144:147], v144 offset:3072
	ds_read_b128 v[148:151], v160
	ds_read_b128 v[152:155], v160 offset:1024
	ds_read_b128 v[156:159], v160 offset:2048
	ds_read_b128 v[160:163], v160 offset:3072
	s_add_u32 s14, s34, 0x160000
	s_addc_u32 s15, s35, 0
	s_mov_b32 m0, s43
	v_lshl_add_u64 v[204:205], s[14:15], 0, v[220:221]
	ds_read_b128 v[164:167], v250 offset:32768
	ds_read_b128 v[168:171], v250 offset:33792
	ds_read_b128 v[172:175], v250 offset:34816
	ds_read_b128 v[176:179], v250 offset:35840
	ds_read_b128 v[180:183], v250 offset:36864
	ds_read_b128 v[184:187], v250 offset:37888
	ds_read_b128 v[188:191], v250 offset:38912
	ds_read_b128 v[192:195], v250 offset:39936
	global_load_lds_dwordx4 v[204:205], off
	v_lshl_add_u64 v[204:205], s[14:15], 0, v[218:219]
	s_mov_b32 m0, s44
	s_nop 0
	global_load_lds_dwordx4 v[204:205], off
	s_waitcnt vmcnt(8)
	s_waitcnt lgkmcnt(0)
	s_barrier
	s_setprio 1
	s_waitcnt lgkmcnt(0)
	v_mfma_f32_16x16x32_bf16 v[128:131], v[132:135], v[164:167], v[128:131]
	v_mfma_f32_16x16x32_bf16 v[128:131], v[136:139], v[168:171], v[128:131]
	v_mfma_f32_16x16x32_bf16 v[112:115], v[132:135], v[172:175], v[112:115]
	v_mfma_f32_16x16x32_bf16 v[112:115], v[136:139], v[176:179], v[112:115]
	v_mfma_f32_16x16x32_bf16 v[96:99], v[132:135], v[180:183], v[96:99]
	v_mfma_f32_16x16x32_bf16 v[96:99], v[136:139], v[184:187], v[96:99]
	v_mfma_f32_16x16x32_bf16 v[80:83], v[132:135], v[188:191], v[80:83]
	v_mfma_f32_16x16x32_bf16 v[80:83], v[136:139], v[192:195], v[80:83]
	v_mfma_f32_16x16x32_bf16 v[124:127], v[140:143], v[164:167], v[124:127]
	v_mfma_f32_16x16x32_bf16 v[124:127], v[144:147], v[168:171], v[124:127]
	v_mfma_f32_16x16x32_bf16 v[108:111], v[140:143], v[172:175], v[108:111]
	v_mfma_f32_16x16x32_bf16 v[108:111], v[144:147], v[176:179], v[108:111]
	v_mfma_f32_16x16x32_bf16 v[92:95], v[140:143], v[180:183], v[92:95]
	v_mfma_f32_16x16x32_bf16 v[92:95], v[144:147], v[184:187], v[92:95]
	v_mfma_f32_16x16x32_bf16 v[76:79], v[140:143], v[188:191], v[76:79]
	v_mfma_f32_16x16x32_bf16 v[76:79], v[144:147], v[192:195], v[76:79]
	s_setprio 0
	s_setprio 1
	v_mfma_f32_16x16x32_bf16 v[120:123], v[148:151], v[164:167], v[120:123]
	v_mfma_f32_16x16x32_bf16 v[120:123], v[152:155], v[168:171], v[120:123]
	v_mfma_f32_16x16x32_bf16 v[104:107], v[148:151], v[172:175], v[104:107]
	v_mfma_f32_16x16x32_bf16 v[104:107], v[152:155], v[176:179], v[104:107]
	v_mfma_f32_16x16x32_bf16 v[88:91], v[148:151], v[180:183], v[88:91]
	v_mfma_f32_16x16x32_bf16 v[88:91], v[152:155], v[184:187], v[88:91]
	v_mfma_f32_16x16x32_bf16 v[72:75], v[148:151], v[188:191], v[72:75]
	v_mfma_f32_16x16x32_bf16 v[72:75], v[152:155], v[192:195], v[72:75]
	v_mfma_f32_16x16x32_bf16 v[116:119], v[156:159], v[164:167], v[116:119]
	v_mfma_f32_16x16x32_bf16 v[116:119], v[160:163], v[168:171], v[116:119]
	v_mfma_f32_16x16x32_bf16 v[100:103], v[156:159], v[172:175], v[100:103]
	v_mfma_f32_16x16x32_bf16 v[100:103], v[160:163], v[176:179], v[100:103]
	v_mfma_f32_16x16x32_bf16 v[84:87], v[156:159], v[180:183], v[84:87]
	v_mfma_f32_16x16x32_bf16 v[84:87], v[160:163], v[184:187], v[84:87]
	v_mfma_f32_16x16x32_bf16 v[68:71], v[156:159], v[188:191], v[68:71]
	v_mfma_f32_16x16x32_bf16 v[68:71], v[160:163], v[192:195], v[68:71]
	s_setprio 0
	s_barrier
	s_mov_b32 m0, s50
	v_lshl_add_u64 v[196:197], v[196:197], 0, s[64:65]
	s_add_u32 s14, s18, 0x160080
	ds_read_b128 v[164:167], v250 offset:49152
	ds_read_b128 v[168:171], v250 offset:50176
	ds_read_b128 v[172:175], v250 offset:51200
	ds_read_b128 v[176:179], v250 offset:52224
	ds_read_b128 v[180:183], v250 offset:53248
	ds_read_b128 v[184:187], v250 offset:54272
	ds_read_b128 v[188:191], v250 offset:55296
	ds_read_b128 v[192:195], v250 offset:56320
	global_load_lds_dwordx4 v[196:197], off
	v_lshl_add_u64 v[196:197], v[198:199], 0, s[64:65]
	s_mov_b32 m0, s51
	s_addc_u32 s15, s19, 0
	global_load_lds_dwordx4 v[196:197], off
	v_lshl_add_u64 v[196:197], s[14:15], 0, v[2:3]
	s_mov_b32 m0, s57
	s_nop 0
	global_load_lds_dwordx4 v[196:197], off
	v_lshl_add_u64 v[196:197], s[14:15], 0, v[216:217]
	s_mov_b32 m0, s58
	s_nop 0
	global_load_lds_dwordx4 v[196:197], off
	v_lshl_add_u64 v[196:197], v[200:201], 0, s[64:65]
	s_mov_b32 m0, s52
	s_nop 0
	global_load_lds_dwordx4 v[196:197], off
	v_lshl_add_u64 v[196:197], v[202:203], 0, s[64:65]
	s_mov_b32 m0, s53
	s_nop 0
	global_load_lds_dwordx4 v[196:197], off
	s_waitcnt vmcnt(8)
	s_waitcnt lgkmcnt(0)
	s_barrier
	s_setprio 1
	s_waitcnt lgkmcnt(0)
	v_mfma_f32_16x16x32_bf16 v[64:67], v[132:135], v[164:167], v[64:67]
	v_mfma_f32_16x16x32_bf16 v[64:67], v[136:139], v[168:171], v[64:67]
	v_mfma_f32_16x16x32_bf16 v[48:51], v[132:135], v[172:175], v[48:51]
	v_mfma_f32_16x16x32_bf16 v[48:51], v[136:139], v[176:179], v[48:51]
	v_mfma_f32_16x16x32_bf16 v[32:35], v[132:135], v[180:183], v[32:35]
	v_mfma_f32_16x16x32_bf16 v[32:35], v[136:139], v[184:187], v[32:35]
	v_mfma_f32_16x16x32_bf16 v[16:19], v[132:135], v[188:191], v[16:19]
	v_mfma_f32_16x16x32_bf16 v[16:19], v[136:139], v[192:195], v[16:19]
	v_mfma_f32_16x16x32_bf16 v[60:63], v[140:143], v[164:167], v[60:63]
	v_mfma_f32_16x16x32_bf16 v[60:63], v[144:147], v[168:171], v[60:63]
	v_mfma_f32_16x16x32_bf16 v[44:47], v[140:143], v[172:175], v[44:47]
	v_mfma_f32_16x16x32_bf16 v[44:47], v[144:147], v[176:179], v[44:47]
	v_mfma_f32_16x16x32_bf16 v[28:31], v[140:143], v[180:183], v[28:31]
	v_mfma_f32_16x16x32_bf16 v[28:31], v[144:147], v[184:187], v[28:31]
	v_mfma_f32_16x16x32_bf16 v[12:15], v[140:143], v[188:191], v[12:15]
	v_mfma_f32_16x16x32_bf16 v[12:15], v[144:147], v[192:195], v[12:15]
	s_setprio 0
	s_setprio 1
	v_mfma_f32_16x16x32_bf16 v[56:59], v[148:151], v[164:167], v[56:59]
	v_mfma_f32_16x16x32_bf16 v[56:59], v[152:155], v[168:171], v[56:59]
	v_mfma_f32_16x16x32_bf16 v[40:43], v[148:151], v[172:175], v[40:43]
	v_mfma_f32_16x16x32_bf16 v[40:43], v[152:155], v[176:179], v[40:43]
	v_mfma_f32_16x16x32_bf16 v[24:27], v[148:151], v[180:183], v[24:27]
	v_mfma_f32_16x16x32_bf16 v[24:27], v[152:155], v[184:187], v[24:27]
	v_mfma_f32_16x16x32_bf16 v[8:11], v[148:151], v[188:191], v[8:11]
	v_mfma_f32_16x16x32_bf16 v[8:11], v[152:155], v[192:195], v[8:11]
	v_mfma_f32_16x16x32_bf16 v[52:55], v[156:159], v[164:167], v[52:55]
	v_mfma_f32_16x16x32_bf16 v[52:55], v[160:163], v[168:171], v[52:55]
	v_mfma_f32_16x16x32_bf16 v[36:39], v[156:159], v[172:175], v[36:39]
	v_mfma_f32_16x16x32_bf16 v[36:39], v[160:163], v[176:179], v[36:39]
	v_mfma_f32_16x16x32_bf16 v[20:23], v[156:159], v[180:183], v[20:23]
	v_mfma_f32_16x16x32_bf16 v[20:23], v[160:163], v[184:187], v[20:23]
	v_mfma_f32_16x16x32_bf16 v[4:7], v[156:159], v[188:191], v[4:7]
	v_mfma_f32_16x16x32_bf16 v[4:7], v[160:163], v[192:195], v[4:7]
	s_setprio 0
	s_barrier
	s_add_i32 s74, s74, 2
	s_add_u32 s71, s71, 0x100
	s_addc_u32 s73, s73, 0
	s_cmpk_gt_u32 s74, 0x55
	s_mov_b64 s[14:15], s[24:25]
	s_cbranch_scc0 .LBB0_3195
	s_and_b64 vcc, exec, s[10:11]
	s_cbranch_vccz .LBB0_3198
	s_barrier
